# blocked forward substitution: the 32 f32-MFMA K-steps interleaved into rows 16..31 of the substitution instead of a separate stage
# baseline (speedup 1.0000x reference)
.LBB0_191:
	s_andn2_saveexec_b64 s[20:21], s[20:21]
	s_cbranch_execz .LBB0_43
	s_movk_i32 s0, 0x7f
	v_cmp_lt_u32_e32 vcc, s0, v49
	s_movk_i32 s0, 0x80
	v_lshlrev_b32_e32 v0, 1, v49
	v_cmp_gt_u32_e64 s[0:1], s0, v49
	v_and_b32_e32 v47, 0x7f, v49
	v_and_b32_e32 v0, 0xffffff00, v0
	v_cndmask_b32_e64 v2, v232, v223, s[0:1]
	v_add_u32_e32 v0, 0x1d700, v0
	v_lshl_or_b32 v2, v47, 1, v2
	v_mov_b32_e32 v3, 0x19100
	v_cndmask_b32_e64 v55, v228, v229, s[0:1]
	v_add_u32_e32 v53, 0, v0
	v_add_u32_e32 v51, 0, v2
	v_add_u32_e32 v57, 0, v3
	v_mov_b32_e32 v85, v1
	v_mov_b32_e32 v0, 0
	v_mov_b32_e32 v2, 0
	v_mov_b32_e32 v3, 0
	v_mov_b32_e32 v4, 0
	v_mov_b32_e32 v5, 0
	v_mov_b32_e32 v6, 0
	v_mov_b32_e32 v7, 0
	v_mov_b32_e32 v8, 0
	v_mov_b32_e32 v9, 0
	v_mov_b32_e32 v10, 0
	v_mov_b32_e32 v11, 0
	v_mov_b32_e32 v12, 0
	v_mov_b32_e32 v13, 0
	v_mov_b32_e32 v14, 0
	v_mov_b32_e32 v15, 0
	v_mov_b32_e32 v16, 0
	v_mov_b32_e32 v17, 0
	v_mov_b32_e32 v18, 0
	v_mov_b32_e32 v19, 0
	v_mov_b32_e32 v20, 0
	v_mov_b32_e32 v21, 0
	v_mov_b32_e32 v22, 0
	v_mov_b32_e32 v23, 0
	v_mov_b32_e32 v24, 0
	v_mov_b32_e32 v25, 0
	v_mov_b32_e32 v26, 0
	v_mov_b32_e32 v27, 0
	v_mov_b32_e32 v28, 0
	v_mov_b32_e32 v29, 0
	v_mov_b32_e32 v30, 0
	v_mov_b32_e32 v31, 0
	v_mov_b32_e32 v32, 0
	v_mov_b32_e32 v33, 0
	v_mov_b32_e32 v34, 0
	v_mov_b32_e32 v35, 0
	v_mov_b32_e32 v36, 0
	v_mov_b32_e32 v37, 0
	v_mov_b32_e32 v86, 0
	v_mov_b32_e32 v87, 0
	v_mov_b32_e32 v88, 0
	v_mov_b32_e32 v89, 0
	v_mov_b32_e32 v90, 0
	v_mov_b32_e32 v91, 0
	v_mov_b32_e32 v92, 0
	v_mov_b32_e32 v93, 0
	v_mov_b32_e32 v94, 0
	v_mov_b32_e32 v95, 0
	v_mov_b32_e32 v96, 0
	v_mov_b32_e32 v97, 0
	v_mov_b32_e32 v98, 0
	v_mov_b32_e32 v99, 0
	v_mov_b32_e32 v100, 0
	v_mov_b32_e32 v101, 0
	v_mov_b32_e32 v102, 0
	v_mov_b32_e32 v103, 0
	v_mov_b32_e32 v104, 0
	v_mov_b32_e32 v105, 0
	v_mov_b32_e32 v106, 0
	v_mov_b32_e32 v107, 0
	v_mov_b32_e32 v108, 0
	v_mov_b32_e32 v109, 0
	v_mov_b32_e32 v110, 0
	v_mov_b32_e32 v111, 0
	v_mov_b32_e32 v112, 0
	v_mov_b32_e32 v113, 0
	ds_read_u16 v221, v51
	ds_read_b32 v220, v53
	ds_read_b128 v[174:177], v57 offset:272
	v_mad_u32_u24 v61, v55, 1, v51
	ds_read_u16 v227, v61
	ds_read_b32 v226, v53 offset:4
	ds_read_b128 v[178:181], v57 offset:544
	v_mad_u32_u24 v61, v55, 2, v51
	ds_read_u16 v59, v61
	ds_read_b32 v204, v53 offset:8
	ds_read_b128 v[182:185], v57 offset:816
	s_waitcnt lgkmcnt(5)
	v_lshlrev_b32_e32 v221, 16, v221
	v_mul_f32_e32 v0, v220, v221
	v_mov_b32_e32 v2, v0
	v_mad_u32_u24 v61, v55, 3, v51
	ds_read_u16 v221, v61
	ds_read_b32 v220, v53 offset:12
	ds_read_b128 v[186:189], v57 offset:1088
	v_pk_fma_f32 v[250:251], v[174:175], v[2:3], 0 op_sel_hi:[1,1,0]
	v_pk_fma_f32 v[202:203], v[176:177], v[4:5], 0 op_sel_hi:[1,1,0]
	v_add_f32_e32 v250, v250, v251
	v_add_f32_e32 v202, v202, v203
	s_waitcnt lgkmcnt(5)
	v_lshlrev_b32_e32 v227, 16, v227
	v_add_f32_e32 v250, v250, v202
	v_fma_f32 v3, v226, v227, -v250
	v_mad_u32_u24 v61, v55, 4, v51
	ds_read_u16 v227, v61
	ds_read_b32 v226, v53 offset:16
	ds_read_b128 v[190:193], v57 offset:1360
	ds_read_b128 v[194:197], v57 offset:1376
	v_pk_fma_f32 v[246:247], v[178:179], v[2:3], 0 op_sel_hi:[1,1,0]
	v_pk_fma_f32 v[248:249], v[180:181], v[4:5], 0 op_sel_hi:[1,1,0]
	v_add_f32_e32 v246, v246, v247
	v_add_f32_e32 v248, v248, v249
	s_waitcnt lgkmcnt(5)
	v_lshlrev_b32_e32 v59, 16, v59
	v_add_f32_e32 v246, v246, v248
	v_fma_f32 v4, v204, v59, -v246
	v_mad_u32_u24 v61, v55, 5, v51
	ds_read_u16 v59, v61
	ds_read_b32 v204, v53 offset:20
	ds_read_b128 v[198:201], v57 offset:1632
	ds_read_b128 v[206:209], v57 offset:1648
	v_pk_fma_f32 v[250:251], v[182:183], v[2:3], 0 op_sel_hi:[1,1,0]
	v_pk_fma_f32 v[202:203], v[184:185], v[4:5], 0 op_sel_hi:[1,1,0]
	v_add_f32_e32 v250, v250, v251
	v_add_f32_e32 v202, v202, v203
	v_lshlrev_b32_e32 v221, 16, v221
	v_add_f32_e32 v250, v250, v202
	v_fma_f32 v5, v220, v221, -v250
	v_mad_u32_u24 v61, v55, 6, v51
	ds_read_u16 v221, v61
	ds_read_b32 v220, v53 offset:24
	ds_read_b128 v[210:213], v57 offset:1904
	ds_read_b128 v[214:217], v57 offset:1920
	s_waitcnt lgkmcnt(5)
	v_pk_fma_f32 v[246:247], v[186:187], v[2:3], 0 op_sel_hi:[1,1,0]
	v_pk_fma_f32 v[248:249], v[188:189], v[4:5], 0 op_sel_hi:[1,1,0]
	v_pk_fma_f32 v[250:251], v[190:191], v[2:3], 0 op_sel_hi:[1,1,0]
	v_pk_fma_f32 v[202:203], v[192:193], v[4:5], 0 op_sel_hi:[1,1,0]
	v_add_f32_e32 v246, v246, v247
	v_add_f32_e32 v248, v248, v249
	v_lshlrev_b32_e32 v227, 16, v227
	v_add_f32_e32 v246, v246, v248
	v_fma_f32 v6, v226, v227, -v246
	v_mad_u32_u24 v61, v55, 7, v51
	ds_read_u16 v227, v61
	ds_read_b32 v226, v53 offset:28
	ds_read_b128 v[238:241], v57 offset:2176
	ds_read_b128 v[242:245], v57 offset:2192
	v_pk_fma_f32 v[250:251], v[194:195], v[6:7], v[250:251]
	v_pk_fma_f32 v[202:203], v[196:197], v[8:9], v[202:203]
	v_pk_fma_f32 v[246:247], v[198:199], v[2:3], 0 op_sel_hi:[1,1,0]
	v_pk_fma_f32 v[248:249], v[200:201], v[4:5], 0 op_sel_hi:[1,1,0]
	v_add_f32_e32 v250, v250, v251
	v_add_f32_e32 v202, v202, v203
	v_lshlrev_b32_e32 v59, 16, v59
	v_add_f32_e32 v250, v250, v202
	v_fma_f32 v7, v204, v59, -v250
	v_mad_u32_u24 v61, v55, 8, v51
	ds_read_u16 v59, v61
	ds_read_b32 v204, v53 offset:32
	ds_read_b128 v[174:177], v57 offset:2448
	ds_read_b128 v[178:181], v57 offset:2464
	s_waitcnt lgkmcnt(5)
	v_pk_fma_f32 v[246:247], v[206:207], v[6:7], v[246:247]
	v_pk_fma_f32 v[248:249], v[208:209], v[8:9], v[248:249]
	ds_read_b128 v[182:185], v57 offset:2480
	v_pk_fma_f32 v[250:251], v[210:211], v[2:3], 0 op_sel_hi:[1,1,0]
	v_pk_fma_f32 v[202:203], v[212:213], v[4:5], 0 op_sel_hi:[1,1,0]
	v_add_f32_e32 v246, v246, v247
	v_add_f32_e32 v248, v248, v249
	v_lshlrev_b32_e32 v221, 16, v221
	v_add_f32_e32 v246, v246, v248
	v_fma_f32 v8, v220, v221, -v246
	v_mad_u32_u24 v61, v55, 9, v51
	ds_read_u16 v221, v61
	ds_read_b32 v220, v53 offset:36
	ds_read_b128 v[186:189], v57 offset:2720
	ds_read_b128 v[190:193], v57 offset:2736
	ds_read_b128 v[194:197], v57 offset:2752
	v_pk_fma_f32 v[250:251], v[214:215], v[6:7], v[250:251]
	v_pk_fma_f32 v[202:203], v[216:217], v[8:9], v[202:203]
	v_pk_fma_f32 v[246:247], v[238:239], v[2:3], 0 op_sel_hi:[1,1,0]
	v_pk_fma_f32 v[248:249], v[240:241], v[4:5], 0 op_sel_hi:[1,1,0]
	v_add_f32_e32 v250, v250, v251
	v_add_f32_e32 v202, v202, v203
	v_lshlrev_b32_e32 v227, 16, v227
	v_add_f32_e32 v250, v250, v202
	v_fma_f32 v9, v226, v227, -v250
	v_mad_u32_u24 v61, v55, 10, v51
	ds_read_u16 v227, v61
	ds_read_b32 v226, v53 offset:40
	s_waitcnt lgkmcnt(5)
	v_pk_fma_f32 v[246:247], v[242:243], v[6:7], v[246:247]
	v_pk_fma_f32 v[248:249], v[244:245], v[8:9], v[248:249]
	ds_read_b128 v[198:201], v57 offset:2992
	ds_read_b128 v[206:209], v57 offset:3008
	ds_read_b128 v[210:213], v57 offset:3024
	v_pk_fma_f32 v[250:251], v[174:175], v[2:3], 0 op_sel_hi:[1,1,0]
	v_pk_fma_f32 v[202:203], v[176:177], v[4:5], 0 op_sel_hi:[1,1,0]
	v_add_f32_e32 v246, v246, v247
	v_pk_fma_f32 v[250:251], v[178:179], v[6:7], v[250:251]
	v_pk_fma_f32 v[202:203], v[180:181], v[8:9], v[202:203]
	v_add_f32_e32 v248, v248, v249
	v_lshlrev_b32_e32 v59, 16, v59
	v_add_f32_e32 v246, v246, v248
	v_fma_f32 v10, v204, v59, -v246
	v_mad_u32_u24 v61, v55, 11, v51
	ds_read_u16 v59, v61
	ds_read_b32 v204, v53 offset:44
	ds_read_b128 v[214:217], v57 offset:3264
	ds_read_b128 v[238:241], v57 offset:3280
	ds_read_b128 v[242:245], v57 offset:3296
	v_pk_fma_f32 v[250:251], v[182:183], v[10:11], v[250:251]
	v_pk_fma_f32 v[202:203], v[184:185], v[12:13], v[202:203]
	s_waitcnt lgkmcnt(5)
	v_pk_fma_f32 v[246:247], v[186:187], v[2:3], 0 op_sel_hi:[1,1,0]
	v_pk_fma_f32 v[248:249], v[188:189], v[4:5], 0 op_sel_hi:[1,1,0]
	v_add_f32_e32 v250, v250, v251
	v_pk_fma_f32 v[246:247], v[190:191], v[6:7], v[246:247]
	v_pk_fma_f32 v[248:249], v[192:193], v[8:9], v[248:249]
	v_add_f32_e32 v202, v202, v203
	v_lshlrev_b32_e32 v221, 16, v221
	v_add_f32_e32 v250, v250, v202
	v_fma_f32 v11, v220, v221, -v250
	v_mad_u32_u24 v61, v55, 12, v51
	ds_read_u16 v221, v61
	ds_read_b32 v220, v53 offset:48
	ds_read_b128 v[174:177], v57 offset:3536
	ds_read_b128 v[178:181], v57 offset:3552
	ds_read_b128 v[182:185], v57 offset:3568
	ds_read_b128 v[186:189], v57 offset:3584
	v_pk_fma_f32 v[246:247], v[194:195], v[10:11], v[246:247]
	v_pk_fma_f32 v[248:249], v[196:197], v[12:13], v[248:249]
	v_pk_fma_f32 v[250:251], v[198:199], v[2:3], 0 op_sel_hi:[1,1,0]
	v_pk_fma_f32 v[202:203], v[200:201], v[4:5], 0 op_sel_hi:[1,1,0]
	v_add_f32_e32 v246, v246, v247
	v_pk_fma_f32 v[250:251], v[206:207], v[6:7], v[250:251]
	v_pk_fma_f32 v[202:203], v[208:209], v[8:9], v[202:203]
	v_add_f32_e32 v248, v248, v249
	v_lshlrev_b32_e32 v227, 16, v227
	v_add_f32_e32 v246, v246, v248
	v_fma_f32 v12, v226, v227, -v246
	v_mad_u32_u24 v61, v55, 13, v51
	ds_read_u16 v227, v61
	ds_read_b32 v226, v53 offset:52
	v_pk_fma_f32 v[250:251], v[210:211], v[10:11], v[250:251]
	v_pk_fma_f32 v[202:203], v[212:213], v[12:13], v[202:203]
	s_waitcnt lgkmcnt(5)
	v_pk_fma_f32 v[246:247], v[214:215], v[2:3], 0 op_sel_hi:[1,1,0]
	v_pk_fma_f32 v[248:249], v[216:217], v[4:5], 0 op_sel_hi:[1,1,0]
	ds_read_b128 v[190:193], v57 offset:3808
	ds_read_b128 v[194:197], v57 offset:3824
	ds_read_b128 v[198:201], v57 offset:3840
	ds_read_b128 v[206:209], v57 offset:3856
	v_add_f32_e32 v250, v250, v251
	v_pk_fma_f32 v[246:247], v[238:239], v[6:7], v[246:247]
	v_pk_fma_f32 v[248:249], v[240:241], v[8:9], v[248:249]
	v_add_f32_e32 v202, v202, v203
	v_lshlrev_b32_e32 v59, 16, v59
	v_add_f32_e32 v250, v250, v202
	v_fma_f32 v13, v204, v59, -v250
	v_mad_u32_u24 v61, v55, 14, v51
	ds_read_u16 v59, v61
	ds_read_b32 v204, v53 offset:56
	ds_read_b128 v[210:213], v57 offset:4080
	ds_read_b128 v[214:217], v57 offset:4096
	v_pk_fma_f32 v[246:247], v[242:243], v[10:11], v[246:247]
	v_pk_fma_f32 v[248:249], v[244:245], v[12:13], v[248:249]
	v_pk_fma_f32 v[250:251], v[174:175], v[2:3], 0 op_sel_hi:[1,1,0]
	v_pk_fma_f32 v[202:203], v[176:177], v[4:5], 0 op_sel_hi:[1,1,0]
	v_add_f32_e32 v246, v246, v247
	s_waitcnt lgkmcnt(5)
	v_pk_fma_f32 v[250:251], v[178:179], v[6:7], v[250:251]
	v_pk_fma_f32 v[202:203], v[180:181], v[8:9], v[202:203]
	ds_read_b128 v[238:241], v57 offset:4112
	ds_read_b128 v[242:245], v57 offset:4128
	v_add_f32_e32 v248, v248, v249
	v_pk_fma_f32 v[250:251], v[182:183], v[10:11], v[250:251]
	v_pk_fma_f32 v[202:203], v[184:185], v[12:13], v[202:203]
	v_lshlrev_b32_e32 v221, 16, v221
	v_add_f32_e32 v246, v246, v248
	v_fma_f32 v14, v220, v221, -v246
	v_mad_u32_u24 v61, v55, 15, v51
	ds_read_u16 v221, v61
	ds_read_b32 v220, v53 offset:60
	v_and_b32_e32 v93, 31, v222
	v_mul_u32_u24_e32 v93, 0x110, v93
	v_lshrrev_b32_e32 v92, 5, v222
	v_lshl_add_u32 v92, v92, 2, v93
	v_add_u32_e32 v92, v92, v57
	v_pk_fma_f32 v[250:251], v[186:187], v[14:15], v[250:251]
	v_pk_fma_f32 v[202:203], v[188:189], v[16:17], v[202:203]
	v_pk_fma_f32 v[246:247], v[190:191], v[2:3], 0 op_sel_hi:[1,1,0]
	v_pk_fma_f32 v[248:249], v[192:193], v[4:5], 0 op_sel_hi:[1,1,0]
	ds_read_b128 v[190:193], v57 offset:4352
	v_add_f32_e32 v250, v250, v251
	v_pk_fma_f32 v[246:247], v[194:195], v[6:7], v[246:247]
	v_pk_fma_f32 v[248:249], v[196:197], v[8:9], v[248:249]
	ds_read_b128 v[194:197], v57 offset:4368
	v_add_f32_e32 v202, v202, v203
	v_pk_fma_f32 v[246:247], v[198:199], v[10:11], v[246:247]
	v_pk_fma_f32 v[248:249], v[200:201], v[12:13], v[248:249]
	ds_read_b128 v[198:201], v57 offset:4384
	v_lshlrev_b32_e32 v227, 16, v227
	v_add_f32_e32 v250, v250, v202
	v_fma_f32 v15, v226, v227, -v250
	ds_read_b32 v94, v92 offset:8704
	s_waitcnt lgkmcnt(5)
	v_pk_fma_f32 v[246:247], v[206:207], v[14:15], v[246:247]
	v_pk_fma_f32 v[248:249], v[208:209], v[16:17], v[248:249]
	ds_read_b128 v[206:209], v57 offset:4400
	v_mad_u32_u24 v61, v55, 16, v51
	ds_read_u16 v227, v61
	ds_read_b32 v226, v53 offset:64
	v_pk_fma_f32 v[250:251], v[210:211], v[2:3], 0 op_sel_hi:[1,1,0]
	v_pk_fma_f32 v[202:203], v[212:213], v[4:5], 0 op_sel_hi:[1,1,0]
	ds_read_b128 v[210:213], v57 offset:4624
	v_add_f32_e32 v246, v246, v247
	v_pk_fma_f32 v[250:251], v[214:215], v[6:7], v[250:251]
	v_pk_fma_f32 v[202:203], v[216:217], v[8:9], v[202:203]
	ds_read_b128 v[214:217], v57 offset:4640
	v_add_f32_e32 v248, v248, v249
	v_pk_fma_f32 v[250:251], v[238:239], v[10:11], v[250:251]
	v_pk_fma_f32 v[202:203], v[240:241], v[12:13], v[202:203]
	ds_read_b128 v[238:241], v57 offset:4656
	v_lshlrev_b32_e32 v59, 16, v59
	v_add_f32_e32 v246, v246, v248
	v_fma_f32 v16, v204, v59, -v246
	ds_read_b32 v95, v92 offset:8712
	v_pk_fma_f32 v[250:251], v[242:243], v[14:15], v[250:251]
	v_pk_fma_f32 v[202:203], v[244:245], v[16:17], v[202:203]
	ds_read_b128 v[242:245], v57 offset:4672
	s_waitcnt lgkmcnt(5)
	v_pk_fma_f32 v[246:247], v[190:191], v[2:3], 0 op_sel_hi:[1,1,0]
	v_pk_fma_f32 v[248:249], v[192:193], v[4:5], 0 op_sel_hi:[1,1,0]
	ds_read_b128 v[190:193], v57 offset:4688
	v_mad_u32_u24 v61, v55, 17, v51
	ds_read_u16 v59, v61
	ds_read_b32 v204, v53 offset:68
	v_add_f32_e32 v250, v250, v251
	v_pk_fma_f32 v[246:247], v[194:195], v[6:7], v[246:247]
	v_pk_fma_f32 v[248:249], v[196:197], v[8:9], v[248:249]
	ds_read_b128 v[194:197], v57 offset:4896
	v_add_f32_e32 v202, v202, v203
	v_pk_fma_f32 v[246:247], v[198:199], v[10:11], v[246:247]
	v_pk_fma_f32 v[248:249], v[200:201], v[12:13], v[248:249]
	ds_read_b128 v[198:201], v57 offset:4912
	v_lshlrev_b32_e32 v221, 16, v221
	v_add_f32_e32 v250, v250, v202
	v_fma_f32 v17, v220, v221, -v250
	ds_read_b32 v96, v92 offset:8720
	v_pk_fma_f32 v[246:247], v[206:207], v[14:15], v[246:247]
	v_pk_fma_f32 v[248:249], v[208:209], v[16:17], v[248:249]
	ds_read_b128 v[206:209], v57 offset:4928
	s_waitcnt lgkmcnt(5)
	v_pk_fma_f32 v[250:251], v[210:211], v[2:3], 0 op_sel_hi:[1,1,0]
	v_pk_fma_f32 v[202:203], v[212:213], v[4:5], 0 op_sel_hi:[1,1,0]
	ds_read_b128 v[210:213], v57 offset:4944
	v_add_f32_e32 v246, v246, v247
	v_pk_fma_f32 v[250:251], v[214:215], v[6:7], v[250:251]
	v_pk_fma_f32 v[202:203], v[216:217], v[8:9], v[202:203]
	ds_read_b128 v[214:217], v57 offset:4960
	v_mad_u32_u24 v61, v55, 18, v51
	ds_read_u16 v221, v61
	ds_read_b32 v220, v53 offset:72
	v_add_f32_e32 v248, v248, v249
	v_pk_fma_f32 v[250:251], v[238:239], v[10:11], v[250:251]
	v_pk_fma_f32 v[202:203], v[240:241], v[12:13], v[202:203]
	ds_read_b128 v[238:241], v57 offset:5168
	v_lshlrev_b32_e32 v227, 16, v227
	v_pk_fma_f32 v[250:251], v[242:243], v[14:15], v[250:251]
	v_pk_fma_f32 v[202:203], v[244:245], v[16:17], v[202:203]
	ds_read_b128 v[242:245], v57 offset:5184
	v_add_f32_e32 v246, v246, v248
	v_fma_f32 v18, v226, v227, -v246
	ds_read_b32 v97, v92 offset:8728
	v_mov_b32_e32 v86, v0
	v_mov_b32_e32 v87, v3
	s_nop 1
	v_permlane32_swap_b32_e32 v86, v87
	s_nop 1
	v_mfma_f32_32x32x2_f32 v[174:189], v94, v86, 0
	v_mfma_f32_32x32x2_f32 v[98:113], v94, v87, 0
	v_pk_fma_f32 v[250:251], v[190:191], v[18:19], v[250:251]
	v_pk_fma_f32 v[202:203], v[192:193], v[20:21], v[202:203]
	ds_read_b128 v[190:193], v57 offset:5200
	s_waitcnt lgkmcnt(5)
	v_pk_fma_f32 v[246:247], v[194:195], v[2:3], 0 op_sel_hi:[1,1,0]
	v_pk_fma_f32 v[248:249], v[196:197], v[4:5], 0 op_sel_hi:[1,1,0]
	ds_read_b128 v[194:197], v57 offset:5216
	v_add_f32_e32 v250, v250, v251
	v_pk_fma_f32 v[246:247], v[198:199], v[6:7], v[246:247]
	v_pk_fma_f32 v[248:249], v[200:201], v[8:9], v[248:249]
	ds_read_b128 v[198:201], v57 offset:5232
	v_mad_u32_u24 v61, v55, 19, v51
	ds_read_u16 v227, v61
	ds_read_b32 v226, v53 offset:76
	v_add_f32_e32 v202, v202, v203
	v_pk_fma_f32 v[246:247], v[206:207], v[10:11], v[246:247]
	v_pk_fma_f32 v[248:249], v[208:209], v[12:13], v[248:249]
	ds_read_b128 v[206:209], v57 offset:5440
	v_lshlrev_b32_e32 v59, 16, v59
	v_pk_fma_f32 v[246:247], v[210:211], v[14:15], v[246:247]
	v_pk_fma_f32 v[248:249], v[212:213], v[16:17], v[248:249]
	ds_read_b128 v[210:213], v57 offset:5456
	v_add_f32_e32 v250, v250, v202
	v_fma_f32 v19, v204, v59, -v250
	ds_read_b32 v34, v92 offset:8736
	v_mov_b32_e32 v88, v4
	v_mov_b32_e32 v89, v5
	s_nop 1
	v_permlane32_swap_b32_e32 v88, v89
	s_nop 1
	v_mfma_f32_32x32x2_f32 v[174:189], v95, v88, v[174:189]
	v_mfma_f32_32x32x2_f32 v[98:113], v95, v89, v[98:113]
	v_pk_fma_f32 v[246:247], v[214:215], v[18:19], v[246:247]
	v_pk_fma_f32 v[248:249], v[216:217], v[20:21], v[248:249]
	ds_read_b128 v[214:217], v57 offset:5472
	s_waitcnt lgkmcnt(5)
	v_pk_fma_f32 v[250:251], v[238:239], v[2:3], 0 op_sel_hi:[1,1,0]
	v_pk_fma_f32 v[202:203], v[240:241], v[4:5], 0 op_sel_hi:[1,1,0]
	ds_read_b128 v[238:241], v57 offset:5488
	v_add_f32_e32 v246, v246, v247
	v_pk_fma_f32 v[250:251], v[242:243], v[6:7], v[250:251]
	v_pk_fma_f32 v[202:203], v[244:245], v[8:9], v[202:203]
	ds_read_b128 v[242:245], v57 offset:5504
	v_mad_u32_u24 v61, v55, 20, v51
	ds_read_u16 v59, v61
	ds_read_b32 v204, v53 offset:80
	v_add_f32_e32 v248, v248, v249
	v_pk_fma_f32 v[250:251], v[190:191], v[10:11], v[250:251]
	v_pk_fma_f32 v[202:203], v[192:193], v[12:13], v[202:203]
	ds_read_b128 v[190:193], v57 offset:5712
	v_lshlrev_b32_e32 v221, 16, v221
	v_pk_fma_f32 v[250:251], v[194:195], v[14:15], v[250:251]
	v_pk_fma_f32 v[202:203], v[196:197], v[16:17], v[202:203]
	ds_read_b128 v[194:197], v57 offset:5728
	v_add_f32_e32 v246, v246, v248
	v_fma_f32 v20, v220, v221, -v246
	ds_read_b32 v35, v92 offset:8744
	v_mov_b32_e32 v90, v6
	v_mov_b32_e32 v91, v7
	s_nop 1
	v_permlane32_swap_b32_e32 v90, v91
	s_nop 1
	v_mfma_f32_32x32x2_f32 v[174:189], v96, v90, v[174:189]
	v_mfma_f32_32x32x2_f32 v[98:113], v96, v91, v[98:113]
	v_pk_fma_f32 v[250:251], v[198:199], v[18:19], v[250:251]
	v_pk_fma_f32 v[202:203], v[200:201], v[20:21], v[202:203]
	ds_read_b128 v[198:201], v57 offset:5744
	s_waitcnt lgkmcnt(5)
	v_pk_fma_f32 v[246:247], v[206:207], v[2:3], 0 op_sel_hi:[1,1,0]
	v_pk_fma_f32 v[248:249], v[208:209], v[4:5], 0 op_sel_hi:[1,1,0]
	ds_read_b128 v[206:209], v57 offset:5760
	v_add_f32_e32 v250, v250, v251
	v_pk_fma_f32 v[246:247], v[210:211], v[6:7], v[246:247]
	v_pk_fma_f32 v[248:249], v[212:213], v[8:9], v[248:249]
	ds_read_b128 v[210:213], v57 offset:5776
	v_add_f32_e32 v202, v202, v203
	v_pk_fma_f32 v[246:247], v[214:215], v[10:11], v[246:247]
	v_pk_fma_f32 v[248:249], v[216:217], v[12:13], v[248:249]
	ds_read_b128 v[214:217], v57 offset:5792
	v_mad_u32_u24 v61, v55, 21, v51
	ds_read_u16 v221, v61
	ds_read_b32 v220, v53 offset:84
	v_lshlrev_b32_e32 v227, 16, v227
	v_pk_fma_f32 v[246:247], v[238:239], v[14:15], v[246:247]
	v_pk_fma_f32 v[248:249], v[240:241], v[16:17], v[248:249]
	ds_read_b128 v[238:241], v57 offset:5984
	v_add_f32_e32 v250, v250, v202
	v_fma_f32 v21, v226, v227, -v250
	ds_read_b32 v36, v92 offset:8752
	v_mov_b32_e32 v86, v8
	v_mov_b32_e32 v87, v9
	s_nop 1
	v_permlane32_swap_b32_e32 v86, v87
	s_nop 1
	v_mfma_f32_32x32x2_f32 v[174:189], v97, v86, v[174:189]
	v_mfma_f32_32x32x2_f32 v[98:113], v97, v87, v[98:113]
	v_pk_fma_f32 v[246:247], v[242:243], v[18:19], v[246:247]
	v_pk_fma_f32 v[248:249], v[244:245], v[20:21], v[248:249]
	ds_read_b128 v[242:245], v57 offset:6000
	s_waitcnt lgkmcnt(5)
	v_pk_fma_f32 v[250:251], v[190:191], v[2:3], 0 op_sel_hi:[1,1,0]
	v_pk_fma_f32 v[202:203], v[192:193], v[4:5], 0 op_sel_hi:[1,1,0]
	ds_read_b128 v[190:193], v57 offset:6016
	v_add_f32_e32 v246, v246, v247
	v_pk_fma_f32 v[250:251], v[194:195], v[6:7], v[250:251]
	v_pk_fma_f32 v[202:203], v[196:197], v[8:9], v[202:203]
	ds_read_b128 v[194:197], v57 offset:6032
	v_add_f32_e32 v248, v248, v249
	v_pk_fma_f32 v[250:251], v[198:199], v[10:11], v[250:251]
	v_pk_fma_f32 v[202:203], v[200:201], v[12:13], v[202:203]
	ds_read_b128 v[198:201], v57 offset:6048
	v_lshlrev_b32_e32 v59, 16, v59
	v_pk_fma_f32 v[250:251], v[206:207], v[14:15], v[250:251]
	v_pk_fma_f32 v[202:203], v[208:209], v[16:17], v[202:203]
	ds_read_b128 v[206:209], v57 offset:6064
	v_mad_u32_u24 v61, v55, 22, v51
	ds_read_u16 v227, v61
	ds_read_b32 v226, v53 offset:88
	v_add_f32_e32 v246, v246, v248
	v_pk_fma_f32 v[250:251], v[210:211], v[18:19], v[250:251]
	v_pk_fma_f32 v[202:203], v[212:213], v[20:21], v[202:203]
	ds_read_b128 v[210:213], v57 offset:6256
	v_fma_f32 v22, v204, v59, -v246
	ds_read_b32 v37, v92 offset:8760
	v_mov_b32_e32 v88, v10
	v_mov_b32_e32 v89, v11
	s_nop 1
	v_permlane32_swap_b32_e32 v88, v89
	s_nop 1
	v_mfma_f32_32x32x2_f32 v[174:189], v34, v88, v[174:189]
	v_mfma_f32_32x32x2_f32 v[98:113], v34, v89, v[98:113]
	v_pk_fma_f32 v[250:251], v[214:215], v[22:23], v[250:251]
	v_pk_fma_f32 v[202:203], v[216:217], v[24:25], v[202:203]
	s_waitcnt lgkmcnt(5)
	v_pk_fma_f32 v[246:247], v[238:239], v[2:3], 0 op_sel_hi:[1,1,0]
	v_pk_fma_f32 v[248:249], v[240:241], v[4:5], 0 op_sel_hi:[1,1,0]
	ds_read_b128 v[214:217], v57 offset:6272
	ds_read_b128 v[238:241], v57 offset:6288
	v_add_f32_e32 v250, v250, v251
	v_pk_fma_f32 v[246:247], v[242:243], v[6:7], v[246:247]
	v_pk_fma_f32 v[248:249], v[244:245], v[8:9], v[248:249]
	ds_read_b128 v[242:245], v57 offset:6304
	v_add_f32_e32 v202, v202, v203
	v_pk_fma_f32 v[246:247], v[190:191], v[10:11], v[246:247]
	v_pk_fma_f32 v[248:249], v[192:193], v[12:13], v[248:249]
	ds_read_b128 v[190:193], v57 offset:6320
	v_lshlrev_b32_e32 v221, 16, v221
	v_pk_fma_f32 v[246:247], v[194:195], v[14:15], v[246:247]
	v_pk_fma_f32 v[248:249], v[196:197], v[16:17], v[248:249]
	ds_read_b128 v[194:197], v57 offset:6336
	v_mad_u32_u24 v61, v55, 23, v51
	ds_read_u16 v59, v61
	ds_read_b32 v204, v53 offset:92
	v_add_f32_e32 v250, v250, v202
	v_pk_fma_f32 v[246:247], v[198:199], v[18:19], v[246:247]
	v_pk_fma_f32 v[248:249], v[200:201], v[20:21], v[248:249]
	ds_read_b128 v[198:201], v57 offset:6528
	v_fma_f32 v23, v220, v221, -v250
	ds_read_b32 v94, v92 offset:8768
	v_mov_b32_e32 v90, v12
	v_mov_b32_e32 v91, v13
	s_nop 1
	v_permlane32_swap_b32_e32 v90, v91
	s_nop 1
	v_mfma_f32_32x32x2_f32 v[174:189], v35, v90, v[174:189]
	v_mfma_f32_32x32x2_f32 v[98:113], v35, v91, v[98:113]
	s_waitcnt lgkmcnt(5)
	v_pk_fma_f32 v[246:247], v[206:207], v[22:23], v[246:247]
	v_pk_fma_f32 v[248:249], v[208:209], v[24:25], v[248:249]
	ds_read_b128 v[206:209], v57 offset:6544
	v_pk_fma_f32 v[250:251], v[210:211], v[2:3], 0 op_sel_hi:[1,1,0]
	v_pk_fma_f32 v[202:203], v[212:213], v[4:5], 0 op_sel_hi:[1,1,0]
	ds_read_b128 v[210:213], v57 offset:6560
	v_add_f32_e32 v246, v246, v247
	v_pk_fma_f32 v[250:251], v[214:215], v[6:7], v[250:251]
	v_pk_fma_f32 v[202:203], v[216:217], v[8:9], v[202:203]
	ds_read_b128 v[214:217], v57 offset:6576
	v_add_f32_e32 v248, v248, v249
	v_pk_fma_f32 v[250:251], v[238:239], v[10:11], v[250:251]
	v_pk_fma_f32 v[202:203], v[240:241], v[12:13], v[202:203]
	ds_read_b128 v[238:241], v57 offset:6592
	v_lshlrev_b32_e32 v227, 16, v227
	v_pk_fma_f32 v[250:251], v[242:243], v[14:15], v[250:251]
	v_pk_fma_f32 v[202:203], v[244:245], v[16:17], v[202:203]
	ds_read_b128 v[242:245], v57 offset:6608
	v_mad_u32_u24 v61, v55, 24, v51
	ds_read_u16 v221, v61
	ds_read_b32 v220, v53 offset:96
	v_add_f32_e32 v246, v246, v248
	v_pk_fma_f32 v[250:251], v[190:191], v[18:19], v[250:251]
	v_pk_fma_f32 v[202:203], v[192:193], v[20:21], v[202:203]
	ds_read_b128 v[190:193], v57 offset:6800
	v_fma_f32 v24, v226, v227, -v246
	ds_read_b32 v95, v92 offset:8776
	v_mov_b32_e32 v86, v14
	v_mov_b32_e32 v87, v15
	s_nop 1
	v_permlane32_swap_b32_e32 v86, v87
	s_nop 1
	v_mfma_f32_32x32x2_f32 v[174:189], v36, v86, v[174:189]
	v_mfma_f32_32x32x2_f32 v[98:113], v36, v87, v[98:113]
	s_waitcnt lgkmcnt(5)
	v_pk_fma_f32 v[250:251], v[194:195], v[22:23], v[250:251]
	v_pk_fma_f32 v[202:203], v[196:197], v[24:25], v[202:203]
	ds_read_b128 v[194:197], v57 offset:6816
	v_pk_fma_f32 v[246:247], v[198:199], v[2:3], 0 op_sel_hi:[1,1,0]
	v_pk_fma_f32 v[248:249], v[200:201], v[4:5], 0 op_sel_hi:[1,1,0]
	ds_read_b128 v[198:201], v57 offset:6832
	v_add_f32_e32 v250, v250, v251
	v_pk_fma_f32 v[246:247], v[206:207], v[6:7], v[246:247]
	v_pk_fma_f32 v[248:249], v[208:209], v[8:9], v[248:249]
	ds_read_b128 v[206:209], v57 offset:6848
	v_add_f32_e32 v202, v202, v203
	v_pk_fma_f32 v[246:247], v[210:211], v[10:11], v[246:247]
	v_pk_fma_f32 v[248:249], v[212:213], v[12:13], v[248:249]
	ds_read_b128 v[210:213], v57 offset:6864
	v_lshlrev_b32_e32 v59, 16, v59
	v_pk_fma_f32 v[246:247], v[214:215], v[14:15], v[246:247]
	v_pk_fma_f32 v[248:249], v[216:217], v[16:17], v[248:249]
	ds_read_b128 v[214:217], v57 offset:6880
	v_add_f32_e32 v250, v250, v202
	v_pk_fma_f32 v[246:247], v[238:239], v[18:19], v[246:247]
	v_pk_fma_f32 v[248:249], v[240:241], v[20:21], v[248:249]
	ds_read_b128 v[238:241], v57 offset:6896
	v_mad_u32_u24 v61, v55, 25, v51
	ds_read_u16 v227, v61
	ds_read_b32 v226, v53 offset:100
	v_fma_f32 v25, v204, v59, -v250
	ds_read_b32 v96, v92 offset:8784
	v_mov_b32_e32 v88, v16
	v_mov_b32_e32 v89, v17
	s_nop 1
	v_permlane32_swap_b32_e32 v88, v89
	s_nop 1
	v_mfma_f32_32x32x2_f32 v[174:189], v37, v88, v[174:189]
	v_mfma_f32_32x32x2_f32 v[98:113], v37, v89, v[98:113]
	s_waitcnt lgkmcnt(5)
	v_pk_fma_f32 v[246:247], v[242:243], v[22:23], v[246:247]
	v_pk_fma_f32 v[248:249], v[244:245], v[24:25], v[248:249]
	ds_read_b128 v[242:245], v57 offset:7072
	v_pk_fma_f32 v[250:251], v[190:191], v[2:3], 0 op_sel_hi:[1,1,0]
	v_pk_fma_f32 v[202:203], v[192:193], v[4:5], 0 op_sel_hi:[1,1,0]
	ds_read_b128 v[190:193], v57 offset:7088
	v_add_f32_e32 v246, v246, v247
	v_pk_fma_f32 v[250:251], v[194:195], v[6:7], v[250:251]
	v_pk_fma_f32 v[202:203], v[196:197], v[8:9], v[202:203]
	ds_read_b128 v[194:197], v57 offset:7104
	v_add_f32_e32 v248, v248, v249
	v_pk_fma_f32 v[250:251], v[198:199], v[10:11], v[250:251]
	v_pk_fma_f32 v[202:203], v[200:201], v[12:13], v[202:203]
	ds_read_b128 v[198:201], v57 offset:7120
	v_lshlrev_b32_e32 v221, 16, v221
	v_pk_fma_f32 v[250:251], v[206:207], v[14:15], v[250:251]
	v_pk_fma_f32 v[202:203], v[208:209], v[16:17], v[202:203]
	ds_read_b128 v[206:209], v57 offset:7136
	v_add_f32_e32 v246, v246, v248
	v_pk_fma_f32 v[250:251], v[210:211], v[18:19], v[250:251]
	v_pk_fma_f32 v[202:203], v[212:213], v[20:21], v[202:203]
	ds_read_b128 v[210:213], v57 offset:7152
	v_fma_f32 v26, v220, v221, -v246
	s_waitcnt lgkmcnt(5)
	v_pk_fma_f32 v[250:251], v[214:215], v[22:23], v[250:251]
	v_pk_fma_f32 v[202:203], v[216:217], v[24:25], v[202:203]
	ds_read_b128 v[214:217], v57 offset:7168
	v_mad_u32_u24 v61, v55, 26, v51
	ds_read_u16 v59, v61
	ds_read_b32 v204, v53 offset:104
	ds_read_b32 v97, v92 offset:8792
	v_mov_b32_e32 v90, v18
	v_mov_b32_e32 v91, v19
	s_nop 1
	v_permlane32_swap_b32_e32 v90, v91
	s_nop 1
	v_mfma_f32_32x32x2_f32 v[174:189], v94, v90, v[174:189]
	v_mfma_f32_32x32x2_f32 v[98:113], v94, v91, v[98:113]
	v_pk_fma_f32 v[250:251], v[238:239], v[26:27], v[250:251]
	v_pk_fma_f32 v[202:203], v[240:241], v[28:29], v[202:203]
	ds_read_b128 v[238:241], v57 offset:7344
	v_pk_fma_f32 v[246:247], v[242:243], v[2:3], 0 op_sel_hi:[1,1,0]
	v_pk_fma_f32 v[248:249], v[244:245], v[4:5], 0 op_sel_hi:[1,1,0]
	ds_read_b128 v[242:245], v57 offset:7360
	v_add_f32_e32 v250, v250, v251
	s_waitcnt lgkmcnt(5)
	v_pk_fma_f32 v[246:247], v[190:191], v[6:7], v[246:247]
	v_pk_fma_f32 v[248:249], v[192:193], v[8:9], v[248:249]
	ds_read_b128 v[190:193], v57 offset:7376
	v_add_f32_e32 v202, v202, v203
	v_pk_fma_f32 v[246:247], v[194:195], v[10:11], v[246:247]
	v_pk_fma_f32 v[248:249], v[196:197], v[12:13], v[248:249]
	ds_read_b128 v[194:197], v57 offset:7392
	v_lshlrev_b32_e32 v227, 16, v227
	v_pk_fma_f32 v[246:247], v[198:199], v[14:15], v[246:247]
	v_pk_fma_f32 v[248:249], v[200:201], v[16:17], v[248:249]
	ds_read_b128 v[198:201], v57 offset:7408
	v_add_f32_e32 v250, v250, v202
	v_pk_fma_f32 v[246:247], v[206:207], v[18:19], v[246:247]
	v_pk_fma_f32 v[248:249], v[208:209], v[20:21], v[248:249]
	ds_read_b128 v[206:209], v57 offset:7424
	v_fma_f32 v27, v226, v227, -v250
	v_pk_fma_f32 v[246:247], v[210:211], v[22:23], v[246:247]
	v_pk_fma_f32 v[248:249], v[212:213], v[24:25], v[248:249]
	ds_read_b128 v[210:213], v57 offset:7440
	v_mad_u32_u24 v61, v55, 27, v51
	ds_read_u16 v221, v61
	ds_read_b32 v220, v53 offset:108
	ds_read_b32 v34, v92 offset:8800
	v_mov_b32_e32 v86, v20
	v_mov_b32_e32 v87, v21
	s_nop 1
	v_permlane32_swap_b32_e32 v86, v87
	s_nop 1
	v_mfma_f32_32x32x2_f32 v[174:189], v95, v86, v[174:189]
	v_mfma_f32_32x32x2_f32 v[98:113], v95, v87, v[98:113]
	v_pk_fma_f32 v[246:247], v[214:215], v[26:27], v[246:247]
	v_pk_fma_f32 v[248:249], v[216:217], v[28:29], v[248:249]
	s_waitcnt lgkmcnt(5)
	v_pk_fma_f32 v[250:251], v[238:239], v[2:3], 0 op_sel_hi:[1,1,0]
	v_pk_fma_f32 v[202:203], v[240:241], v[4:5], 0 op_sel_hi:[1,1,0]
	ds_read_b128 v[214:217], v57 offset:7616
	ds_read_b128 v[238:241], v57 offset:7632
	v_add_f32_e32 v246, v246, v247
	v_pk_fma_f32 v[250:251], v[242:243], v[6:7], v[250:251]
	v_pk_fma_f32 v[202:203], v[244:245], v[8:9], v[202:203]
	ds_read_b128 v[242:245], v57 offset:7648
	v_add_f32_e32 v248, v248, v249
	v_pk_fma_f32 v[250:251], v[190:191], v[10:11], v[250:251]
	v_pk_fma_f32 v[202:203], v[192:193], v[12:13], v[202:203]
	ds_read_b128 v[190:193], v57 offset:7664
	v_lshlrev_b32_e32 v59, 16, v59
	v_pk_fma_f32 v[250:251], v[194:195], v[14:15], v[250:251]
	v_pk_fma_f32 v[202:203], v[196:197], v[16:17], v[202:203]
	ds_read_b128 v[194:197], v57 offset:7680
	v_add_f32_e32 v246, v246, v248
	v_pk_fma_f32 v[250:251], v[198:199], v[18:19], v[250:251]
	v_pk_fma_f32 v[202:203], v[200:201], v[20:21], v[202:203]
	ds_read_b128 v[198:201], v57 offset:7696
	v_fma_f32 v28, v204, v59, -v246
	s_waitcnt lgkmcnt(5)
	v_pk_fma_f32 v[250:251], v[206:207], v[22:23], v[250:251]
	v_pk_fma_f32 v[202:203], v[208:209], v[24:25], v[202:203]
	ds_read_b128 v[206:209], v57 offset:7712
	v_mad_u32_u24 v61, v55, 28, v51
	ds_read_u16 v227, v61
	ds_read_b32 v226, v53 offset:112
	ds_read_b32 v35, v92 offset:8808
	v_mov_b32_e32 v88, v22
	v_mov_b32_e32 v89, v23
	s_nop 1
	v_permlane32_swap_b32_e32 v88, v89
	s_nop 1
	v_mfma_f32_32x32x2_f32 v[174:189], v96, v88, v[174:189]
	v_mfma_f32_32x32x2_f32 v[98:113], v96, v89, v[98:113]
	v_pk_fma_f32 v[250:251], v[210:211], v[26:27], v[250:251]
	v_pk_fma_f32 v[202:203], v[212:213], v[28:29], v[202:203]
	ds_read_b128 v[210:213], v57 offset:7888
	v_pk_fma_f32 v[246:247], v[214:215], v[2:3], 0 op_sel_hi:[1,1,0]
	v_pk_fma_f32 v[248:249], v[216:217], v[4:5], 0 op_sel_hi:[1,1,0]
	ds_read_b128 v[214:217], v57 offset:7904
	v_add_f32_e32 v250, v250, v251
	s_waitcnt lgkmcnt(5)
	v_pk_fma_f32 v[246:247], v[238:239], v[6:7], v[246:247]
	v_pk_fma_f32 v[248:249], v[240:241], v[8:9], v[248:249]
	ds_read_b128 v[238:241], v57 offset:7920
	v_add_f32_e32 v202, v202, v203
	v_pk_fma_f32 v[246:247], v[242:243], v[10:11], v[246:247]
	v_pk_fma_f32 v[248:249], v[244:245], v[12:13], v[248:249]
	ds_read_b128 v[242:245], v57 offset:7936
	v_lshlrev_b32_e32 v221, 16, v221
	v_pk_fma_f32 v[246:247], v[190:191], v[14:15], v[246:247]
	v_pk_fma_f32 v[248:249], v[192:193], v[16:17], v[248:249]
	ds_read_b128 v[190:193], v57 offset:7952
	v_add_f32_e32 v250, v250, v202
	v_pk_fma_f32 v[246:247], v[194:195], v[18:19], v[246:247]
	v_pk_fma_f32 v[248:249], v[196:197], v[20:21], v[248:249]
	ds_read_b128 v[194:197], v57 offset:7968
	v_fma_f32 v29, v220, v221, -v250
	v_pk_fma_f32 v[246:247], v[198:199], v[22:23], v[246:247]
	v_pk_fma_f32 v[248:249], v[200:201], v[24:25], v[248:249]
	ds_read_b128 v[198:201], v57 offset:7984
	ds_read_b32 v36, v92 offset:8816
	v_mov_b32_e32 v90, v24
	v_mov_b32_e32 v91, v25
	s_nop 1
	v_permlane32_swap_b32_e32 v90, v91
	s_nop 1
	v_mfma_f32_32x32x2_f32 v[174:189], v97, v90, v[174:189]
	v_mfma_f32_32x32x2_f32 v[98:113], v97, v91, v[98:113]
	v_pk_fma_f32 v[246:247], v[206:207], v[26:27], v[246:247]
	v_pk_fma_f32 v[248:249], v[208:209], v[28:29], v[248:249]
	ds_read_b128 v[206:209], v57 offset:8000
	s_waitcnt lgkmcnt(5)
	v_pk_fma_f32 v[250:251], v[210:211], v[2:3], 0 op_sel_hi:[1,1,0]
	v_pk_fma_f32 v[202:203], v[212:213], v[4:5], 0 op_sel_hi:[1,1,0]
	v_mad_u32_u24 v61, v55, 29, v51
	ds_read_u16 v59, v61
	ds_read_b32 v204, v53 offset:116
	ds_read_b128 v[210:213], v57 offset:8160
	v_add_f32_e32 v246, v246, v247
	v_pk_fma_f32 v[250:251], v[214:215], v[6:7], v[250:251]
	v_pk_fma_f32 v[202:203], v[216:217], v[8:9], v[202:203]
	ds_read_b128 v[214:217], v57 offset:8176
	v_add_f32_e32 v248, v248, v249
	v_pk_fma_f32 v[250:251], v[238:239], v[10:11], v[250:251]
	v_pk_fma_f32 v[202:203], v[240:241], v[12:13], v[202:203]
	ds_read_b128 v[238:241], v57 offset:8192
	v_lshlrev_b32_e32 v227, 16, v227
	v_pk_fma_f32 v[250:251], v[242:243], v[14:15], v[250:251]
	v_pk_fma_f32 v[202:203], v[244:245], v[16:17], v[202:203]
	ds_read_b128 v[242:245], v57 offset:8208
	v_add_f32_e32 v246, v246, v248
	s_waitcnt lgkmcnt(5)
	v_pk_fma_f32 v[250:251], v[190:191], v[18:19], v[250:251]
	v_pk_fma_f32 v[202:203], v[192:193], v[20:21], v[202:203]
	ds_read_b128 v[190:193], v57 offset:8224
	v_fma_f32 v30, v226, v227, -v246
	v_pk_fma_f32 v[250:251], v[194:195], v[22:23], v[250:251]
	v_pk_fma_f32 v[202:203], v[196:197], v[24:25], v[202:203]
	ds_read_b128 v[194:197], v57 offset:8240
	v_pk_fma_f32 v[250:251], v[198:199], v[26:27], v[250:251]
	v_pk_fma_f32 v[202:203], v[200:201], v[28:29], v[202:203]
	ds_read_b128 v[198:201], v57 offset:8256
	ds_read_b32 v37, v92 offset:8824
	v_mov_b32_e32 v86, v26
	v_mov_b32_e32 v87, v27
	s_nop 1
	v_permlane32_swap_b32_e32 v86, v87
	s_nop 1
	v_mfma_f32_32x32x2_f32 v[174:189], v34, v86, v[174:189]
	v_mfma_f32_32x32x2_f32 v[98:113], v34, v87, v[98:113]
	v_pk_fma_f32 v[250:251], v[206:207], v[30:31], v[250:251]
	v_pk_fma_f32 v[202:203], v[208:209], v[32:33], v[202:203]
	ds_read_b128 v[206:209], v57 offset:8272
	v_mad_u32_u24 v61, v55, 30, v51
	ds_read_u16 v221, v61
	ds_read_b32 v220, v53 offset:120
	s_waitcnt lgkmcnt(5)
	v_pk_fma_f32 v[246:247], v[210:211], v[2:3], 0 op_sel_hi:[1,1,0]
	v_pk_fma_f32 v[248:249], v[212:213], v[4:5], 0 op_sel_hi:[1,1,0]
	ds_read_b128 v[210:213], v57 offset:8432
	v_add_f32_e32 v250, v250, v251
	v_pk_fma_f32 v[246:247], v[214:215], v[6:7], v[246:247]
	v_pk_fma_f32 v[248:249], v[216:217], v[8:9], v[248:249]
	ds_read_b128 v[214:217], v57 offset:8448
	v_add_f32_e32 v202, v202, v203
	v_pk_fma_f32 v[246:247], v[238:239], v[10:11], v[246:247]
	v_pk_fma_f32 v[248:249], v[240:241], v[12:13], v[248:249]
	ds_read_b128 v[238:241], v57 offset:8464
	v_lshlrev_b32_e32 v59, 16, v59
	v_pk_fma_f32 v[246:247], v[242:243], v[14:15], v[246:247]
	v_pk_fma_f32 v[248:249], v[244:245], v[16:17], v[248:249]
	ds_read_b128 v[242:245], v57 offset:8480
	v_add_f32_e32 v250, v250, v202
	v_pk_fma_f32 v[246:247], v[190:191], v[18:19], v[246:247]
	v_pk_fma_f32 v[248:249], v[192:193], v[20:21], v[248:249]
	ds_read_b128 v[190:193], v57 offset:8496
	v_fma_f32 v31, v204, v59, -v250
	v_pk_fma_f32 v[246:247], v[194:195], v[22:23], v[246:247]
	v_pk_fma_f32 v[248:249], v[196:197], v[24:25], v[248:249]
	ds_read_b128 v[194:197], v57 offset:8512
	s_waitcnt lgkmcnt(5)
	v_pk_fma_f32 v[246:247], v[198:199], v[26:27], v[246:247]
	v_pk_fma_f32 v[248:249], v[200:201], v[28:29], v[248:249]
	ds_read_b128 v[198:201], v57 offset:8528
	v_mov_b32_e32 v88, v28
	v_mov_b32_e32 v89, v29
	s_nop 1
	v_permlane32_swap_b32_e32 v88, v89
	s_nop 1
	v_mfma_f32_32x32x2_f32 v[174:189], v35, v88, v[174:189]
	v_mfma_f32_32x32x2_f32 v[98:113], v35, v89, v[98:113]
	v_pk_fma_f32 v[246:247], v[206:207], v[30:31], v[246:247]
	v_pk_fma_f32 v[248:249], v[208:209], v[32:33], v[248:249]
	ds_read_b128 v[206:209], v57 offset:8544
	v_mad_u32_u24 v61, v55, 31, v51
	ds_read_u16 v227, v61
	ds_read_b32 v226, v53 offset:124
	v_mad_u32_u24 v61, v55, 32, v51
	ds_read_u16 v59, v61
	ds_read_b32 v204, v53 offset:128
	v_pk_fma_f32 v[250:251], v[210:211], v[2:3], 0 op_sel_hi:[1,1,0]
	v_pk_fma_f32 v[202:203], v[212:213], v[4:5], 0 op_sel_hi:[1,1,0]
	ds_read_b128 v[210:213], v57 offset:9104
	v_add_f32_e32 v246, v246, v247
	s_waitcnt lgkmcnt(5)
	v_pk_fma_f32 v[250:251], v[214:215], v[6:7], v[250:251]
	v_pk_fma_f32 v[202:203], v[216:217], v[8:9], v[202:203]
	v_add_f32_e32 v248, v248, v249
	v_pk_fma_f32 v[250:251], v[238:239], v[10:11], v[250:251]
	v_pk_fma_f32 v[202:203], v[240:241], v[12:13], v[202:203]
	v_lshlrev_b32_e32 v221, 16, v221
	v_pk_fma_f32 v[250:251], v[242:243], v[14:15], v[250:251]
	v_pk_fma_f32 v[202:203], v[244:245], v[16:17], v[202:203]
	v_add_f32_e32 v246, v246, v248
	v_pk_fma_f32 v[250:251], v[190:191], v[18:19], v[250:251]
	v_pk_fma_f32 v[202:203], v[192:193], v[20:21], v[202:203]
	v_fma_f32 v32, v220, v221, -v246
	v_mad_u32_u24 v61, v55, 33, v51
	ds_read_u16 v221, v61
	ds_read_b32 v220, v53 offset:132
	ds_read_b128 v[214:217], v57 offset:9376
	v_pk_fma_f32 v[250:251], v[194:195], v[22:23], v[250:251]
	v_pk_fma_f32 v[202:203], v[196:197], v[24:25], v[202:203]
	v_pk_fma_f32 v[250:251], v[198:199], v[26:27], v[250:251]
	v_pk_fma_f32 v[202:203], v[200:201], v[28:29], v[202:203]
	v_mov_b32_e32 v90, v30
	v_mov_b32_e32 v91, v31
	s_nop 1
	v_permlane32_swap_b32_e32 v90, v91
	s_nop 1
	v_mfma_f32_32x32x2_f32 v[174:189], v36, v90, v[174:189]
	v_mfma_f32_32x32x2_f32 v[98:113], v36, v91, v[98:113]
	v_pk_fma_f32 v[250:251], v[206:207], v[30:31], v[250:251]
	v_pk_fma_f32 v[202:203], v[208:209], v[32:33], v[202:203]
	v_add_f32_e32 v250, v250, v251
	v_add_f32_e32 v202, v202, v203
	s_waitcnt lgkmcnt(5)
	v_lshlrev_b32_e32 v227, 16, v227
	v_add_f32_e32 v250, v250, v202
	v_fma_f32 v33, v226, v227, -v250
	v_mad_u32_u24 v61, v55, 34, v51
	ds_read_u16 v227, v61
	ds_read_b32 v226, v53 offset:136
	ds_read_b128 v[238:241], v57 offset:9648
	v_mov_b32_e32 v86, v32
	v_mov_b32_e32 v87, v33
	s_nop 1
	v_permlane32_swap_b32_e32 v86, v87
	s_nop 1
	v_mfma_f32_32x32x2_f32 v[174:189], v37, v86, v[174:189]
	v_mfma_f32_32x32x2_f32 v[98:113], v37, v87, v[98:113]
	s_nop 15
	s_nop 7
	v_permlane32_swap_b32_e32 v174, v98
	v_permlane32_swap_b32_e32 v175, v99
	v_permlane32_swap_b32_e32 v176, v100
	v_permlane32_swap_b32_e32 v177, v101
	v_permlane32_swap_b32_e32 v178, v102
	v_permlane32_swap_b32_e32 v179, v103
	v_permlane32_swap_b32_e32 v180, v104
	v_permlane32_swap_b32_e32 v181, v105
	v_permlane32_swap_b32_e32 v182, v106
	v_permlane32_swap_b32_e32 v183, v107
	v_permlane32_swap_b32_e32 v184, v108
	v_permlane32_swap_b32_e32 v185, v109
	v_permlane32_swap_b32_e32 v186, v110
	v_permlane32_swap_b32_e32 v187, v111
	v_permlane32_swap_b32_e32 v188, v112
	v_permlane32_swap_b32_e32 v189, v113
	s_waitcnt lgkmcnt(5)
	v_lshlrev_b32_e32 v59, 16, v59
	v_fma_f32 v34, v204, v59, -v174
	v_mad_u32_u24 v61, v55, 35, v51
	ds_read_u16 v59, v61
	ds_read_b32 v204, v53 offset:140
	ds_read_b128 v[242:245], v57 offset:9920
	v_pk_fma_f32 v[250:251], v[210:211], v[34:35], 0 op_sel_hi:[1,1,0]
	v_pk_fma_f32 v[202:203], v[212:213], v[36:37], 0 op_sel_hi:[1,1,0]
	v_add_f32_e32 v250, v250, v251
	v_add_f32_e32 v202, v202, v203
	s_waitcnt lgkmcnt(5)
	v_lshlrev_b32_e32 v221, 16, v221
	v_add_f32_e32 v250, v250, v202
	v_add_f32_e32 v250, v250, v175
	v_fma_f32 v35, v220, v221, -v250
	v_mad_u32_u24 v61, v55, 36, v51
	ds_read_u16 v221, v61
	ds_read_b32 v220, v53 offset:144
	ds_read_b128 v[190:193], v57 offset:10192
	ds_read_b128 v[194:197], v57 offset:10208
	v_pk_fma_f32 v[246:247], v[214:215], v[34:35], 0 op_sel_hi:[1,1,0]
	v_pk_fma_f32 v[248:249], v[216:217], v[36:37], 0 op_sel_hi:[1,1,0]
	v_add_f32_e32 v246, v246, v247
	v_add_f32_e32 v248, v248, v249
	s_waitcnt lgkmcnt(5)
	v_lshlrev_b32_e32 v227, 16, v227
	v_add_f32_e32 v246, v246, v248
	v_add_f32_e32 v246, v246, v176
	v_fma_f32 v36, v226, v227, -v246
	v_mad_u32_u24 v61, v55, 37, v51
	ds_read_u16 v227, v61
	ds_read_b32 v226, v53 offset:148
	ds_read_b128 v[198:201], v57 offset:10464
	ds_read_b128 v[206:209], v57 offset:10480
	v_pk_fma_f32 v[250:251], v[238:239], v[34:35], 0 op_sel_hi:[1,1,0]
	v_pk_fma_f32 v[202:203], v[240:241], v[36:37], 0 op_sel_hi:[1,1,0]
	v_add_f32_e32 v250, v250, v251
	v_add_f32_e32 v202, v202, v203
	v_lshlrev_b32_e32 v59, 16, v59
	v_add_f32_e32 v250, v250, v202
	v_add_f32_e32 v250, v250, v177
	v_fma_f32 v37, v204, v59, -v250
	v_mad_u32_u24 v61, v55, 38, v51
	ds_read_u16 v59, v61
	ds_read_b32 v204, v53 offset:152
	ds_read_b128 v[210:213], v57 offset:10736
	ds_read_b128 v[214:217], v57 offset:10752
	s_waitcnt lgkmcnt(5)
	v_pk_fma_f32 v[246:247], v[242:243], v[34:35], 0 op_sel_hi:[1,1,0]
	v_pk_fma_f32 v[248:249], v[244:245], v[36:37], 0 op_sel_hi:[1,1,0]
	v_pk_fma_f32 v[250:251], v[190:191], v[34:35], 0 op_sel_hi:[1,1,0]
	v_pk_fma_f32 v[202:203], v[192:193], v[36:37], 0 op_sel_hi:[1,1,0]
	v_add_f32_e32 v246, v246, v247
	v_add_f32_e32 v248, v248, v249
	v_lshlrev_b32_e32 v221, 16, v221
	v_add_f32_e32 v246, v246, v248
	v_add_f32_e32 v246, v246, v98
	v_fma_f32 v86, v220, v221, -v246
	v_mad_u32_u24 v61, v55, 39, v51
	ds_read_u16 v221, v61
	ds_read_b32 v220, v53 offset:156
	ds_read_b128 v[238:241], v57 offset:11008
	ds_read_b128 v[242:245], v57 offset:11024
	v_pk_fma_f32 v[250:251], v[194:195], v[86:87], v[250:251]
	v_pk_fma_f32 v[202:203], v[196:197], v[88:89], v[202:203]
	v_pk_fma_f32 v[246:247], v[198:199], v[34:35], 0 op_sel_hi:[1,1,0]
	v_pk_fma_f32 v[248:249], v[200:201], v[36:37], 0 op_sel_hi:[1,1,0]
	v_add_f32_e32 v250, v250, v251
	v_add_f32_e32 v202, v202, v203
	v_lshlrev_b32_e32 v227, 16, v227
	v_add_f32_e32 v250, v250, v202
	v_add_f32_e32 v250, v250, v99
	v_fma_f32 v87, v226, v227, -v250
	v_mad_u32_u24 v61, v55, 40, v51
	ds_read_u16 v227, v61
	ds_read_b32 v226, v53 offset:160
	ds_read_b128 v[190:193], v57 offset:11280
	ds_read_b128 v[194:197], v57 offset:11296
	s_waitcnt lgkmcnt(5)
	v_pk_fma_f32 v[246:247], v[206:207], v[86:87], v[246:247]
	v_pk_fma_f32 v[248:249], v[208:209], v[88:89], v[248:249]
	ds_read_b128 v[198:201], v57 offset:11312
	v_pk_fma_f32 v[250:251], v[210:211], v[34:35], 0 op_sel_hi:[1,1,0]
	v_pk_fma_f32 v[202:203], v[212:213], v[36:37], 0 op_sel_hi:[1,1,0]
	v_add_f32_e32 v246, v246, v247
	v_add_f32_e32 v248, v248, v249
	v_lshlrev_b32_e32 v59, 16, v59
	v_add_f32_e32 v246, v246, v248
	v_add_f32_e32 v246, v246, v100
	v_fma_f32 v88, v204, v59, -v246
	v_mad_u32_u24 v61, v55, 41, v51
	ds_read_u16 v59, v61
	ds_read_b32 v204, v53 offset:164
	ds_read_b128 v[206:209], v57 offset:11552
	ds_read_b128 v[210:213], v57 offset:11568
	v_pk_fma_f32 v[250:251], v[214:215], v[86:87], v[250:251]
	v_pk_fma_f32 v[202:203], v[216:217], v[88:89], v[202:203]
	ds_read_b128 v[214:217], v57 offset:11584
	v_pk_fma_f32 v[246:247], v[238:239], v[34:35], 0 op_sel_hi:[1,1,0]
	v_pk_fma_f32 v[248:249], v[240:241], v[36:37], 0 op_sel_hi:[1,1,0]
	v_add_f32_e32 v250, v250, v251
	v_add_f32_e32 v202, v202, v203
	v_lshlrev_b32_e32 v221, 16, v221
	v_add_f32_e32 v250, v250, v202
	v_add_f32_e32 v250, v250, v101
	v_fma_f32 v89, v220, v221, -v250
	v_mad_u32_u24 v61, v55, 42, v51
	ds_read_u16 v221, v61
	ds_read_b32 v220, v53 offset:168
	s_waitcnt lgkmcnt(5)
	v_pk_fma_f32 v[246:247], v[242:243], v[86:87], v[246:247]
	v_pk_fma_f32 v[248:249], v[244:245], v[88:89], v[248:249]
	ds_read_b128 v[238:241], v57 offset:11824
	ds_read_b128 v[242:245], v57 offset:11840
	v_pk_fma_f32 v[250:251], v[190:191], v[34:35], 0 op_sel_hi:[1,1,0]
	v_pk_fma_f32 v[202:203], v[192:193], v[36:37], 0 op_sel_hi:[1,1,0]
	ds_read_b128 v[190:193], v57 offset:11856
	v_add_f32_e32 v246, v246, v247
	v_pk_fma_f32 v[250:251], v[194:195], v[86:87], v[250:251]
	v_pk_fma_f32 v[202:203], v[196:197], v[88:89], v[202:203]
	v_add_f32_e32 v248, v248, v249
	v_lshlrev_b32_e32 v227, 16, v227
	v_add_f32_e32 v246, v246, v248
	v_add_f32_e32 v246, v246, v178
	v_fma_f32 v90, v226, v227, -v246
	v_mad_u32_u24 v61, v55, 43, v51
	ds_read_u16 v227, v61
	ds_read_b32 v226, v53 offset:172
	ds_read_b128 v[194:197], v57 offset:12096
	v_pk_fma_f32 v[250:251], v[198:199], v[90:91], v[250:251]
	v_pk_fma_f32 v[202:203], v[200:201], v[92:93], v[202:203]
	ds_read_b128 v[198:201], v57 offset:12112
	s_waitcnt lgkmcnt(5)
	v_pk_fma_f32 v[246:247], v[206:207], v[34:35], 0 op_sel_hi:[1,1,0]
	v_pk_fma_f32 v[248:249], v[208:209], v[36:37], 0 op_sel_hi:[1,1,0]
	ds_read_b128 v[206:209], v57 offset:12128
	v_add_f32_e32 v250, v250, v251
	v_pk_fma_f32 v[246:247], v[210:211], v[86:87], v[246:247]
	v_pk_fma_f32 v[248:249], v[212:213], v[88:89], v[248:249]
	v_add_f32_e32 v202, v202, v203
	v_lshlrev_b32_e32 v59, 16, v59
	v_add_f32_e32 v250, v250, v202
	v_add_f32_e32 v250, v250, v179
	v_fma_f32 v91, v204, v59, -v250
	v_mad_u32_u24 v61, v55, 44, v51
	ds_read_u16 v59, v61
	ds_read_b32 v204, v53 offset:176
	ds_read_b128 v[210:213], v57 offset:12368
	v_pk_fma_f32 v[246:247], v[214:215], v[90:91], v[246:247]
	v_pk_fma_f32 v[248:249], v[216:217], v[92:93], v[248:249]
	ds_read_b128 v[214:217], v57 offset:12384
	v_pk_fma_f32 v[250:251], v[238:239], v[34:35], 0 op_sel_hi:[1,1,0]
	v_pk_fma_f32 v[202:203], v[240:241], v[36:37], 0 op_sel_hi:[1,1,0]
	ds_read_b128 v[238:241], v57 offset:12400
	v_add_f32_e32 v246, v246, v247
	v_pk_fma_f32 v[250:251], v[242:243], v[86:87], v[250:251]
	v_pk_fma_f32 v[202:203], v[244:245], v[88:89], v[202:203]
	ds_read_b128 v[242:245], v57 offset:12416
	v_add_f32_e32 v248, v248, v249
	v_lshlrev_b32_e32 v221, 16, v221
	v_add_f32_e32 v246, v246, v248
	v_add_f32_e32 v246, v246, v180
	v_fma_f32 v92, v220, v221, -v246
	s_waitcnt lgkmcnt(5)
	v_pk_fma_f32 v[250:251], v[190:191], v[90:91], v[250:251]
	v_pk_fma_f32 v[202:203], v[192:193], v[92:93], v[202:203]
	v_mad_u32_u24 v61, v55, 45, v51
	ds_read_u16 v221, v61
	ds_read_b32 v220, v53 offset:180
	ds_read_b128 v[190:193], v57 offset:12640
	v_pk_fma_f32 v[246:247], v[194:195], v[34:35], 0 op_sel_hi:[1,1,0]
	v_pk_fma_f32 v[248:249], v[196:197], v[36:37], 0 op_sel_hi:[1,1,0]
	ds_read_b128 v[194:197], v57 offset:12656
	v_add_f32_e32 v250, v250, v251
	v_pk_fma_f32 v[246:247], v[198:199], v[86:87], v[246:247]
	v_pk_fma_f32 v[248:249], v[200:201], v[88:89], v[248:249]
	ds_read_b128 v[198:201], v57 offset:12672
	v_add_f32_e32 v202, v202, v203
	v_lshlrev_b32_e32 v227, 16, v227
	v_add_f32_e32 v250, v250, v202
	v_add_f32_e32 v250, v250, v181
	v_fma_f32 v93, v226, v227, -v250
	v_pk_fma_f32 v[246:247], v[206:207], v[90:91], v[246:247]
	v_pk_fma_f32 v[248:249], v[208:209], v[92:93], v[248:249]
	ds_read_b128 v[206:209], v57 offset:12688
	v_mad_u32_u24 v61, v55, 46, v51
	ds_read_u16 v227, v61
	ds_read_b32 v226, v53 offset:184
	s_waitcnt lgkmcnt(5)
	v_pk_fma_f32 v[250:251], v[210:211], v[34:35], 0 op_sel_hi:[1,1,0]
	v_pk_fma_f32 v[202:203], v[212:213], v[36:37], 0 op_sel_hi:[1,1,0]
	ds_read_b128 v[210:213], v57 offset:12912
	v_add_f32_e32 v246, v246, v247
	v_pk_fma_f32 v[250:251], v[214:215], v[86:87], v[250:251]
	v_pk_fma_f32 v[202:203], v[216:217], v[88:89], v[202:203]
	ds_read_b128 v[214:217], v57 offset:12928
	v_add_f32_e32 v248, v248, v249
	v_pk_fma_f32 v[250:251], v[238:239], v[90:91], v[250:251]
	v_pk_fma_f32 v[202:203], v[240:241], v[92:93], v[202:203]
	ds_read_b128 v[238:241], v57 offset:12944
	v_lshlrev_b32_e32 v59, 16, v59
	v_add_f32_e32 v246, v246, v248
	v_add_f32_e32 v246, v246, v102
	v_fma_f32 v94, v204, v59, -v246
	v_pk_fma_f32 v[250:251], v[242:243], v[94:95], v[250:251]
	v_pk_fma_f32 v[202:203], v[244:245], v[96:97], v[202:203]
	ds_read_b128 v[242:245], v57 offset:12960
	v_mad_u32_u24 v61, v55, 47, v51
	ds_read_u16 v59, v61
	ds_read_b32 v204, v53 offset:188
	v_pk_fma_f32 v[246:247], v[190:191], v[34:35], 0 op_sel_hi:[1,1,0]
	v_pk_fma_f32 v[248:249], v[192:193], v[36:37], 0 op_sel_hi:[1,1,0]
	ds_read_b128 v[190:193], v57 offset:13184
	v_add_f32_e32 v250, v250, v251
	s_waitcnt lgkmcnt(5)
	v_pk_fma_f32 v[246:247], v[194:195], v[86:87], v[246:247]
	v_pk_fma_f32 v[248:249], v[196:197], v[88:89], v[248:249]
	ds_read_b128 v[194:197], v57 offset:13200
	v_add_f32_e32 v202, v202, v203
	v_pk_fma_f32 v[246:247], v[198:199], v[90:91], v[246:247]
	v_pk_fma_f32 v[248:249], v[200:201], v[92:93], v[248:249]
	ds_read_b128 v[198:201], v57 offset:13216
	v_lshlrev_b32_e32 v221, 16, v221
	v_add_f32_e32 v250, v250, v202
	v_add_f32_e32 v250, v250, v103
	v_fma_f32 v95, v220, v221, -v250
	v_pk_fma_f32 v[246:247], v[206:207], v[94:95], v[246:247]
	v_pk_fma_f32 v[248:249], v[208:209], v[96:97], v[248:249]
	ds_read_b128 v[206:209], v57 offset:13232
	v_mad_u32_u24 v61, v55, 48, v51
	ds_read_u16 v221, v61
	ds_read_b32 v220, v53 offset:192
	v_pk_fma_f32 v[250:251], v[210:211], v[34:35], 0 op_sel_hi:[1,1,0]
	v_pk_fma_f32 v[202:203], v[212:213], v[36:37], 0 op_sel_hi:[1,1,0]
	ds_read_b128 v[210:213], v57 offset:13456
	v_add_f32_e32 v246, v246, v247
	v_pk_fma_f32 v[250:251], v[214:215], v[86:87], v[250:251]
	v_pk_fma_f32 v[202:203], v[216:217], v[88:89], v[202:203]
	ds_read_b128 v[214:217], v57 offset:13472
	v_add_f32_e32 v248, v248, v249
	s_waitcnt lgkmcnt(5)
	v_pk_fma_f32 v[250:251], v[238:239], v[90:91], v[250:251]
	v_pk_fma_f32 v[202:203], v[240:241], v[92:93], v[202:203]
	ds_read_b128 v[238:241], v57 offset:13488
	v_lshlrev_b32_e32 v227, 16, v227
	v_add_f32_e32 v246, v246, v248
	v_add_f32_e32 v246, v246, v104
	v_fma_f32 v96, v226, v227, -v246
	v_pk_fma_f32 v[250:251], v[242:243], v[94:95], v[250:251]
	v_pk_fma_f32 v[202:203], v[244:245], v[96:97], v[202:203]
	ds_read_b128 v[242:245], v57 offset:13504
	v_pk_fma_f32 v[246:247], v[190:191], v[34:35], 0 op_sel_hi:[1,1,0]
	v_pk_fma_f32 v[248:249], v[192:193], v[36:37], 0 op_sel_hi:[1,1,0]
	ds_read_b128 v[190:193], v57 offset:13520
	v_mad_u32_u24 v61, v55, 49, v51
	ds_read_u16 v227, v61
	ds_read_b32 v226, v53 offset:196
	v_add_f32_e32 v250, v250, v251
	v_pk_fma_f32 v[246:247], v[194:195], v[86:87], v[246:247]
	v_pk_fma_f32 v[248:249], v[196:197], v[88:89], v[248:249]
	ds_read_b128 v[194:197], v57 offset:13728
	v_add_f32_e32 v202, v202, v203
	v_pk_fma_f32 v[246:247], v[198:199], v[90:91], v[246:247]
	v_pk_fma_f32 v[248:249], v[200:201], v[92:93], v[248:249]
	ds_read_b128 v[198:201], v57 offset:13744
	v_lshlrev_b32_e32 v59, 16, v59
	v_add_f32_e32 v250, v250, v202
	v_add_f32_e32 v250, v250, v105
	v_fma_f32 v97, v204, v59, -v250
	s_waitcnt lgkmcnt(5)
	v_pk_fma_f32 v[246:247], v[206:207], v[94:95], v[246:247]
	v_pk_fma_f32 v[248:249], v[208:209], v[96:97], v[248:249]
	ds_read_b128 v[206:209], v57 offset:13760
	v_pk_fma_f32 v[250:251], v[210:211], v[34:35], 0 op_sel_hi:[1,1,0]
	v_pk_fma_f32 v[202:203], v[212:213], v[36:37], 0 op_sel_hi:[1,1,0]
	ds_read_b128 v[210:213], v57 offset:13776
	v_add_f32_e32 v246, v246, v247
	v_pk_fma_f32 v[250:251], v[214:215], v[86:87], v[250:251]
	v_pk_fma_f32 v[202:203], v[216:217], v[88:89], v[202:203]
	ds_read_b128 v[214:217], v57 offset:13792
	v_mad_u32_u24 v61, v55, 50, v51
	ds_read_u16 v59, v61
	ds_read_b32 v204, v53 offset:200
	v_add_f32_e32 v248, v248, v249
	v_pk_fma_f32 v[250:251], v[238:239], v[90:91], v[250:251]
	v_pk_fma_f32 v[202:203], v[240:241], v[92:93], v[202:203]
	ds_read_b128 v[238:241], v57 offset:14000
	v_lshlrev_b32_e32 v221, 16, v221
	v_pk_fma_f32 v[250:251], v[242:243], v[94:95], v[250:251]
	v_pk_fma_f32 v[202:203], v[244:245], v[96:97], v[202:203]
	ds_read_b128 v[242:245], v57 offset:14016
	v_add_f32_e32 v246, v246, v248
	v_add_f32_e32 v246, v246, v182
	v_fma_f32 v98, v220, v221, -v246
	s_waitcnt lgkmcnt(5)
	v_pk_fma_f32 v[250:251], v[190:191], v[98:99], v[250:251]
	v_pk_fma_f32 v[202:203], v[192:193], v[100:101], v[202:203]
	ds_read_b128 v[190:193], v57 offset:14032
	v_pk_fma_f32 v[246:247], v[194:195], v[34:35], 0 op_sel_hi:[1,1,0]
	v_pk_fma_f32 v[248:249], v[196:197], v[36:37], 0 op_sel_hi:[1,1,0]
	ds_read_b128 v[194:197], v57 offset:14048
	v_add_f32_e32 v250, v250, v251
	v_pk_fma_f32 v[246:247], v[198:199], v[86:87], v[246:247]
	v_pk_fma_f32 v[248:249], v[200:201], v[88:89], v[248:249]
	ds_read_b128 v[198:201], v57 offset:14064
	v_mad_u32_u24 v61, v55, 51, v51
	ds_read_u16 v221, v61
	ds_read_b32 v220, v53 offset:204
	v_add_f32_e32 v202, v202, v203
	v_pk_fma_f32 v[246:247], v[206:207], v[90:91], v[246:247]
	v_pk_fma_f32 v[248:249], v[208:209], v[92:93], v[248:249]
	ds_read_b128 v[206:209], v57 offset:14272
	v_lshlrev_b32_e32 v227, 16, v227
	v_pk_fma_f32 v[246:247], v[210:211], v[94:95], v[246:247]
	v_pk_fma_f32 v[248:249], v[212:213], v[96:97], v[248:249]
	ds_read_b128 v[210:213], v57 offset:14288
	v_add_f32_e32 v250, v250, v202
	v_add_f32_e32 v250, v250, v183
	v_fma_f32 v99, v226, v227, -v250
	s_waitcnt lgkmcnt(5)
	v_pk_fma_f32 v[246:247], v[214:215], v[98:99], v[246:247]
	v_pk_fma_f32 v[248:249], v[216:217], v[100:101], v[248:249]
	ds_read_b128 v[214:217], v57 offset:14304
	v_pk_fma_f32 v[250:251], v[238:239], v[34:35], 0 op_sel_hi:[1,1,0]
	v_pk_fma_f32 v[202:203], v[240:241], v[36:37], 0 op_sel_hi:[1,1,0]
	ds_read_b128 v[238:241], v57 offset:14320
	v_add_f32_e32 v246, v246, v247
	v_pk_fma_f32 v[250:251], v[242:243], v[86:87], v[250:251]
	v_pk_fma_f32 v[202:203], v[244:245], v[88:89], v[202:203]
	ds_read_b128 v[242:245], v57 offset:14336
	v_mad_u32_u24 v61, v55, 52, v51
	ds_read_u16 v227, v61
	ds_read_b32 v226, v53 offset:208
	v_add_f32_e32 v248, v248, v249
	v_pk_fma_f32 v[250:251], v[190:191], v[90:91], v[250:251]
	v_pk_fma_f32 v[202:203], v[192:193], v[92:93], v[202:203]
	ds_read_b128 v[190:193], v57 offset:14544
	v_lshlrev_b32_e32 v59, 16, v59
	v_pk_fma_f32 v[250:251], v[194:195], v[94:95], v[250:251]
	v_pk_fma_f32 v[202:203], v[196:197], v[96:97], v[202:203]
	ds_read_b128 v[194:197], v57 offset:14560
	v_add_f32_e32 v246, v246, v248
	v_add_f32_e32 v246, v246, v184
	v_fma_f32 v100, v204, v59, -v246
	s_waitcnt lgkmcnt(5)
	v_pk_fma_f32 v[250:251], v[198:199], v[98:99], v[250:251]
	v_pk_fma_f32 v[202:203], v[200:201], v[100:101], v[202:203]
	ds_read_b128 v[198:201], v57 offset:14576
	v_pk_fma_f32 v[246:247], v[206:207], v[34:35], 0 op_sel_hi:[1,1,0]
	v_pk_fma_f32 v[248:249], v[208:209], v[36:37], 0 op_sel_hi:[1,1,0]
	ds_read_b128 v[206:209], v57 offset:14592
	v_add_f32_e32 v250, v250, v251
	v_pk_fma_f32 v[246:247], v[210:211], v[86:87], v[246:247]
	v_pk_fma_f32 v[248:249], v[212:213], v[88:89], v[248:249]
	ds_read_b128 v[210:213], v57 offset:14608
	v_add_f32_e32 v202, v202, v203
	v_pk_fma_f32 v[246:247], v[214:215], v[90:91], v[246:247]
	v_pk_fma_f32 v[248:249], v[216:217], v[92:93], v[248:249]
	ds_read_b128 v[214:217], v57 offset:14624
	v_mad_u32_u24 v61, v55, 53, v51
	ds_read_u16 v59, v61
	ds_read_b32 v204, v53 offset:212
	v_lshlrev_b32_e32 v221, 16, v221
	v_pk_fma_f32 v[246:247], v[238:239], v[94:95], v[246:247]
	v_pk_fma_f32 v[248:249], v[240:241], v[96:97], v[248:249]
	ds_read_b128 v[238:241], v57 offset:14816
	v_add_f32_e32 v250, v250, v202
	v_add_f32_e32 v250, v250, v185
	v_fma_f32 v101, v220, v221, -v250
	s_waitcnt lgkmcnt(5)
	v_pk_fma_f32 v[246:247], v[242:243], v[98:99], v[246:247]
	v_pk_fma_f32 v[248:249], v[244:245], v[100:101], v[248:249]
	ds_read_b128 v[242:245], v57 offset:14832
	v_pk_fma_f32 v[250:251], v[190:191], v[34:35], 0 op_sel_hi:[1,1,0]
	v_pk_fma_f32 v[202:203], v[192:193], v[36:37], 0 op_sel_hi:[1,1,0]
	ds_read_b128 v[190:193], v57 offset:14848
	v_add_f32_e32 v246, v246, v247
	v_pk_fma_f32 v[250:251], v[194:195], v[86:87], v[250:251]
	v_pk_fma_f32 v[202:203], v[196:197], v[88:89], v[202:203]
	ds_read_b128 v[194:197], v57 offset:14864
	v_add_f32_e32 v248, v248, v249
	v_pk_fma_f32 v[250:251], v[198:199], v[90:91], v[250:251]
	v_pk_fma_f32 v[202:203], v[200:201], v[92:93], v[202:203]
	ds_read_b128 v[198:201], v57 offset:14880
	v_lshlrev_b32_e32 v227, 16, v227
	v_pk_fma_f32 v[250:251], v[206:207], v[94:95], v[250:251]
	v_pk_fma_f32 v[202:203], v[208:209], v[96:97], v[202:203]
	ds_read_b128 v[206:209], v57 offset:14896
	v_mad_u32_u24 v61, v55, 54, v51
	ds_read_u16 v221, v61
	ds_read_b32 v220, v53 offset:216
	v_add_f32_e32 v246, v246, v248
	s_waitcnt lgkmcnt(5)
	v_pk_fma_f32 v[250:251], v[210:211], v[98:99], v[250:251]
	v_pk_fma_f32 v[202:203], v[212:213], v[100:101], v[202:203]
	ds_read_b128 v[210:213], v57 offset:15088
	v_add_f32_e32 v246, v246, v106
	v_fma_f32 v102, v226, v227, -v246
	v_pk_fma_f32 v[250:251], v[214:215], v[102:103], v[250:251]
	v_pk_fma_f32 v[202:203], v[216:217], v[104:105], v[202:203]
	ds_read_b128 v[214:217], v57 offset:15104
	v_pk_fma_f32 v[246:247], v[238:239], v[34:35], 0 op_sel_hi:[1,1,0]
	v_pk_fma_f32 v[248:249], v[240:241], v[36:37], 0 op_sel_hi:[1,1,0]
	ds_read_b128 v[238:241], v57 offset:15120
	v_add_f32_e32 v250, v250, v251
	v_pk_fma_f32 v[246:247], v[242:243], v[86:87], v[246:247]
	v_pk_fma_f32 v[248:249], v[244:245], v[88:89], v[248:249]
	ds_read_b128 v[242:245], v57 offset:15136
	v_add_f32_e32 v202, v202, v203
	v_pk_fma_f32 v[246:247], v[190:191], v[90:91], v[246:247]
	v_pk_fma_f32 v[248:249], v[192:193], v[92:93], v[248:249]
	ds_read_b128 v[190:193], v57 offset:15152
	v_lshlrev_b32_e32 v59, 16, v59
	s_waitcnt lgkmcnt(5)
	v_pk_fma_f32 v[246:247], v[194:195], v[94:95], v[246:247]
	v_pk_fma_f32 v[248:249], v[196:197], v[96:97], v[248:249]
	ds_read_b128 v[194:197], v57 offset:15168
	v_mad_u32_u24 v61, v55, 55, v51
	ds_read_u16 v227, v61
	ds_read_b32 v226, v53 offset:220
	v_add_f32_e32 v250, v250, v202
	v_pk_fma_f32 v[246:247], v[198:199], v[98:99], v[246:247]
	v_pk_fma_f32 v[248:249], v[200:201], v[100:101], v[248:249]
	ds_read_b128 v[198:201], v57 offset:15360
	v_add_f32_e32 v250, v250, v107
	v_fma_f32 v103, v204, v59, -v250
	v_pk_fma_f32 v[246:247], v[206:207], v[102:103], v[246:247]
	v_pk_fma_f32 v[248:249], v[208:209], v[104:105], v[248:249]
	ds_read_b128 v[206:209], v57 offset:15376
	s_waitcnt lgkmcnt(5)
	v_pk_fma_f32 v[250:251], v[210:211], v[34:35], 0 op_sel_hi:[1,1,0]
	v_pk_fma_f32 v[202:203], v[212:213], v[36:37], 0 op_sel_hi:[1,1,0]
	ds_read_b128 v[210:213], v57 offset:15392
	v_add_f32_e32 v246, v246, v247
	v_pk_fma_f32 v[250:251], v[214:215], v[86:87], v[250:251]
	v_pk_fma_f32 v[202:203], v[216:217], v[88:89], v[202:203]
	ds_read_b128 v[214:217], v57 offset:15408
	v_add_f32_e32 v248, v248, v249
	v_pk_fma_f32 v[250:251], v[238:239], v[90:91], v[250:251]
	v_pk_fma_f32 v[202:203], v[240:241], v[92:93], v[202:203]
	ds_read_b128 v[238:241], v57 offset:15424
	v_lshlrev_b32_e32 v221, 16, v221
	v_pk_fma_f32 v[250:251], v[242:243], v[94:95], v[250:251]
	v_pk_fma_f32 v[202:203], v[244:245], v[96:97], v[202:203]
	ds_read_b128 v[242:245], v57 offset:15440
	v_mad_u32_u24 v61, v55, 56, v51
	ds_read_u16 v59, v61
	ds_read_b32 v204, v53 offset:224
	v_add_f32_e32 v246, v246, v248
	v_pk_fma_f32 v[250:251], v[190:191], v[98:99], v[250:251]
	v_pk_fma_f32 v[202:203], v[192:193], v[100:101], v[202:203]
	ds_read_b128 v[190:193], v57 offset:15632
	v_add_f32_e32 v246, v246, v108
	v_fma_f32 v104, v220, v221, -v246
	s_waitcnt lgkmcnt(5)
	v_pk_fma_f32 v[250:251], v[194:195], v[102:103], v[250:251]
	v_pk_fma_f32 v[202:203], v[196:197], v[104:105], v[202:203]
	ds_read_b128 v[194:197], v57 offset:15648
	v_pk_fma_f32 v[246:247], v[198:199], v[34:35], 0 op_sel_hi:[1,1,0]
	v_pk_fma_f32 v[248:249], v[200:201], v[36:37], 0 op_sel_hi:[1,1,0]
	ds_read_b128 v[198:201], v57 offset:15664
	v_add_f32_e32 v250, v250, v251
	v_pk_fma_f32 v[246:247], v[206:207], v[86:87], v[246:247]
	v_pk_fma_f32 v[248:249], v[208:209], v[88:89], v[248:249]
	ds_read_b128 v[206:209], v57 offset:15680
	v_add_f32_e32 v202, v202, v203
	v_pk_fma_f32 v[246:247], v[210:211], v[90:91], v[246:247]
	v_pk_fma_f32 v[248:249], v[212:213], v[92:93], v[248:249]
	ds_read_b128 v[210:213], v57 offset:15696
	v_lshlrev_b32_e32 v227, 16, v227
	v_pk_fma_f32 v[246:247], v[214:215], v[94:95], v[246:247]
	v_pk_fma_f32 v[248:249], v[216:217], v[96:97], v[248:249]
	ds_read_b128 v[214:217], v57 offset:15712
	v_add_f32_e32 v250, v250, v202
	s_waitcnt lgkmcnt(5)
	v_pk_fma_f32 v[246:247], v[238:239], v[98:99], v[246:247]
	v_pk_fma_f32 v[248:249], v[240:241], v[100:101], v[248:249]
	ds_read_b128 v[238:241], v57 offset:15728
	v_mad_u32_u24 v61, v55, 57, v51
	ds_read_u16 v221, v61
	ds_read_b32 v220, v53 offset:228
	v_add_f32_e32 v250, v250, v109
	v_fma_f32 v105, v226, v227, -v250
	v_pk_fma_f32 v[246:247], v[242:243], v[102:103], v[246:247]
	v_pk_fma_f32 v[248:249], v[244:245], v[104:105], v[248:249]
	ds_read_b128 v[242:245], v57 offset:15904
	v_pk_fma_f32 v[250:251], v[190:191], v[34:35], 0 op_sel_hi:[1,1,0]
	v_pk_fma_f32 v[202:203], v[192:193], v[36:37], 0 op_sel_hi:[1,1,0]
	ds_read_b128 v[190:193], v57 offset:15920
	v_add_f32_e32 v246, v246, v247
	s_waitcnt lgkmcnt(5)
	v_pk_fma_f32 v[250:251], v[194:195], v[86:87], v[250:251]
	v_pk_fma_f32 v[202:203], v[196:197], v[88:89], v[202:203]
	ds_read_b128 v[194:197], v57 offset:15936
	v_add_f32_e32 v248, v248, v249
	v_pk_fma_f32 v[250:251], v[198:199], v[90:91], v[250:251]
	v_pk_fma_f32 v[202:203], v[200:201], v[92:93], v[202:203]
	ds_read_b128 v[198:201], v57 offset:15952
	v_lshlrev_b32_e32 v59, 16, v59
	v_pk_fma_f32 v[250:251], v[206:207], v[94:95], v[250:251]
	v_pk_fma_f32 v[202:203], v[208:209], v[96:97], v[202:203]
	ds_read_b128 v[206:209], v57 offset:15968
	v_add_f32_e32 v246, v246, v248
	v_pk_fma_f32 v[250:251], v[210:211], v[98:99], v[250:251]
	v_pk_fma_f32 v[202:203], v[212:213], v[100:101], v[202:203]
	ds_read_b128 v[210:213], v57 offset:15984
	v_add_f32_e32 v246, v246, v186
	v_pk_fma_f32 v[250:251], v[214:215], v[102:103], v[250:251]
	v_pk_fma_f32 v[202:203], v[216:217], v[104:105], v[202:203]
	ds_read_b128 v[214:217], v57 offset:16000
	v_mad_u32_u24 v61, v55, 58, v51
	ds_read_u16 v227, v61
	ds_read_b32 v226, v53 offset:232
	v_fma_f32 v106, v204, v59, -v246
	s_waitcnt lgkmcnt(5)
	v_pk_fma_f32 v[250:251], v[238:239], v[106:107], v[250:251]
	v_pk_fma_f32 v[202:203], v[240:241], v[108:109], v[202:203]
	ds_read_b128 v[238:241], v57 offset:16176
	v_pk_fma_f32 v[246:247], v[242:243], v[34:35], 0 op_sel_hi:[1,1,0]
	v_pk_fma_f32 v[248:249], v[244:245], v[36:37], 0 op_sel_hi:[1,1,0]
	ds_read_b128 v[242:245], v57 offset:16192
	v_add_f32_e32 v250, v250, v251
	v_pk_fma_f32 v[246:247], v[190:191], v[86:87], v[246:247]
	v_pk_fma_f32 v[248:249], v[192:193], v[88:89], v[248:249]
	ds_read_b128 v[190:193], v57 offset:16208
	v_add_f32_e32 v202, v202, v203
	v_pk_fma_f32 v[246:247], v[194:195], v[90:91], v[246:247]
	v_pk_fma_f32 v[248:249], v[196:197], v[92:93], v[248:249]
	ds_read_b128 v[194:197], v57 offset:16224
	v_lshlrev_b32_e32 v221, 16, v221
	v_pk_fma_f32 v[246:247], v[198:199], v[94:95], v[246:247]
	v_pk_fma_f32 v[248:249], v[200:201], v[96:97], v[248:249]
	ds_read_b128 v[198:201], v57 offset:16240
	v_add_f32_e32 v250, v250, v202
	s_waitcnt lgkmcnt(5)
	v_pk_fma_f32 v[246:247], v[206:207], v[98:99], v[246:247]
	v_pk_fma_f32 v[248:249], v[208:209], v[100:101], v[248:249]
	ds_read_b128 v[206:209], v57 offset:16256
	v_add_f32_e32 v250, v250, v187
	v_pk_fma_f32 v[246:247], v[210:211], v[102:103], v[246:247]
	v_pk_fma_f32 v[248:249], v[212:213], v[104:105], v[248:249]
	ds_read_b128 v[210:213], v57 offset:16272
	v_mad_u32_u24 v61, v55, 59, v51
	ds_read_u16 v59, v61
	ds_read_b32 v204, v53 offset:236
	v_fma_f32 v107, v220, v221, -v250
	v_pk_fma_f32 v[246:247], v[214:215], v[106:107], v[246:247]
	v_pk_fma_f32 v[248:249], v[216:217], v[108:109], v[248:249]
	ds_read_b128 v[214:217], v57 offset:16448
	s_waitcnt lgkmcnt(5)
	v_pk_fma_f32 v[250:251], v[238:239], v[34:35], 0 op_sel_hi:[1,1,0]
	v_pk_fma_f32 v[202:203], v[240:241], v[36:37], 0 op_sel_hi:[1,1,0]
	ds_read_b128 v[238:241], v57 offset:16464
	v_add_f32_e32 v246, v246, v247
	v_pk_fma_f32 v[250:251], v[242:243], v[86:87], v[250:251]
	v_pk_fma_f32 v[202:203], v[244:245], v[88:89], v[202:203]
	ds_read_b128 v[242:245], v57 offset:16480
	v_add_f32_e32 v248, v248, v249
	v_pk_fma_f32 v[250:251], v[190:191], v[90:91], v[250:251]
	v_pk_fma_f32 v[202:203], v[192:193], v[92:93], v[202:203]
	ds_read_b128 v[190:193], v57 offset:16496
	v_lshlrev_b32_e32 v227, 16, v227
	v_pk_fma_f32 v[250:251], v[194:195], v[94:95], v[250:251]
	v_pk_fma_f32 v[202:203], v[196:197], v[96:97], v[202:203]
	ds_read_b128 v[194:197], v57 offset:16512
	v_add_f32_e32 v246, v246, v248
	v_pk_fma_f32 v[250:251], v[198:199], v[98:99], v[250:251]
	v_pk_fma_f32 v[202:203], v[200:201], v[100:101], v[202:203]
	ds_read_b128 v[198:201], v57 offset:16528
	v_add_f32_e32 v246, v246, v188
	s_waitcnt lgkmcnt(5)
	v_pk_fma_f32 v[250:251], v[206:207], v[102:103], v[250:251]
	v_pk_fma_f32 v[202:203], v[208:209], v[104:105], v[202:203]
	ds_read_b128 v[206:209], v57 offset:16544
	v_mad_u32_u24 v61, v55, 60, v51
	ds_read_u16 v221, v61
	ds_read_b32 v220, v53 offset:240
	v_fma_f32 v108, v226, v227, -v246
	v_pk_fma_f32 v[250:251], v[210:211], v[106:107], v[250:251]
	v_pk_fma_f32 v[202:203], v[212:213], v[108:109], v[202:203]
	ds_read_b128 v[210:213], v57 offset:16720
	v_pk_fma_f32 v[246:247], v[214:215], v[34:35], 0 op_sel_hi:[1,1,0]
	v_pk_fma_f32 v[248:249], v[216:217], v[36:37], 0 op_sel_hi:[1,1,0]
	ds_read_b128 v[214:217], v57 offset:16736
	v_add_f32_e32 v250, v250, v251
	s_waitcnt lgkmcnt(5)
	v_pk_fma_f32 v[246:247], v[238:239], v[86:87], v[246:247]
	v_pk_fma_f32 v[248:249], v[240:241], v[88:89], v[248:249]
	ds_read_b128 v[238:241], v57 offset:16752
	v_add_f32_e32 v202, v202, v203
	v_pk_fma_f32 v[246:247], v[242:243], v[90:91], v[246:247]
	v_pk_fma_f32 v[248:249], v[244:245], v[92:93], v[248:249]
	ds_read_b128 v[242:245], v57 offset:16768
	v_lshlrev_b32_e32 v59, 16, v59
	v_pk_fma_f32 v[246:247], v[190:191], v[94:95], v[246:247]
	v_pk_fma_f32 v[248:249], v[192:193], v[96:97], v[248:249]
	ds_read_b128 v[190:193], v57 offset:16784
	v_add_f32_e32 v250, v250, v202
	v_pk_fma_f32 v[246:247], v[194:195], v[98:99], v[246:247]
	v_pk_fma_f32 v[248:249], v[196:197], v[100:101], v[248:249]
	ds_read_b128 v[194:197], v57 offset:16800
	v_add_f32_e32 v250, v250, v189
	v_pk_fma_f32 v[246:247], v[198:199], v[102:103], v[246:247]
	v_pk_fma_f32 v[248:249], v[200:201], v[104:105], v[248:249]
	ds_read_b128 v[198:201], v57 offset:16816
	v_fma_f32 v109, v204, v59, -v250
	s_waitcnt lgkmcnt(5)
	v_pk_fma_f32 v[246:247], v[206:207], v[106:107], v[246:247]
	v_pk_fma_f32 v[248:249], v[208:209], v[108:109], v[248:249]
	ds_read_b128 v[206:209], v57 offset:16832
	v_mad_u32_u24 v61, v55, 61, v51
	ds_read_u16 v227, v61
	ds_read_b32 v226, v53 offset:244
	v_pk_fma_f32 v[250:251], v[210:211], v[34:35], 0 op_sel_hi:[1,1,0]
	v_pk_fma_f32 v[202:203], v[212:213], v[36:37], 0 op_sel_hi:[1,1,0]
	ds_read_b128 v[210:213], v57 offset:16992
	v_add_f32_e32 v246, v246, v247
	v_pk_fma_f32 v[250:251], v[214:215], v[86:87], v[250:251]
	v_pk_fma_f32 v[202:203], v[216:217], v[88:89], v[202:203]
	ds_read_b128 v[214:217], v57 offset:17008
	v_add_f32_e32 v248, v248, v249
	s_waitcnt lgkmcnt(5)
	v_pk_fma_f32 v[250:251], v[238:239], v[90:91], v[250:251]
	v_pk_fma_f32 v[202:203], v[240:241], v[92:93], v[202:203]
	ds_read_b128 v[238:241], v57 offset:17024
	v_lshlrev_b32_e32 v221, 16, v221
	v_pk_fma_f32 v[250:251], v[242:243], v[94:95], v[250:251]
	v_pk_fma_f32 v[202:203], v[244:245], v[96:97], v[202:203]
	ds_read_b128 v[242:245], v57 offset:17040
	v_add_f32_e32 v246, v246, v248
	v_pk_fma_f32 v[250:251], v[190:191], v[98:99], v[250:251]
	v_pk_fma_f32 v[202:203], v[192:193], v[100:101], v[202:203]
	ds_read_b128 v[190:193], v57 offset:17056
	v_add_f32_e32 v246, v246, v110
	v_pk_fma_f32 v[250:251], v[194:195], v[102:103], v[250:251]
	v_pk_fma_f32 v[202:203], v[196:197], v[104:105], v[202:203]
	ds_read_b128 v[194:197], v57 offset:17072
	v_fma_f32 v110, v220, v221, -v246
	v_pk_fma_f32 v[250:251], v[198:199], v[106:107], v[250:251]
	v_pk_fma_f32 v[202:203], v[200:201], v[108:109], v[202:203]
	ds_read_b128 v[198:201], v57 offset:17088
	s_waitcnt lgkmcnt(5)
	v_pk_fma_f32 v[250:251], v[206:207], v[110:111], v[250:251]
	v_pk_fma_f32 v[202:203], v[208:209], v[112:113], v[202:203]
	ds_read_b128 v[206:209], v57 offset:17104
	v_mad_u32_u24 v61, v55, 62, v51
	ds_read_u16 v59, v61
	ds_read_b32 v204, v53 offset:248
	v_pk_fma_f32 v[246:247], v[210:211], v[34:35], 0 op_sel_hi:[1,1,0]
	v_pk_fma_f32 v[248:249], v[212:213], v[36:37], 0 op_sel_hi:[1,1,0]
	ds_read_b128 v[210:213], v57 offset:17264
	v_add_f32_e32 v250, v250, v251
	v_pk_fma_f32 v[246:247], v[214:215], v[86:87], v[246:247]
	v_pk_fma_f32 v[248:249], v[216:217], v[88:89], v[248:249]
	ds_read_b128 v[214:217], v57 offset:17280
	v_add_f32_e32 v202, v202, v203
	s_waitcnt lgkmcnt(5)
	v_pk_fma_f32 v[246:247], v[238:239], v[90:91], v[246:247]
	v_pk_fma_f32 v[248:249], v[240:241], v[92:93], v[248:249]
	ds_read_b128 v[238:241], v57 offset:17296
	v_lshlrev_b32_e32 v227, 16, v227
	v_pk_fma_f32 v[246:247], v[242:243], v[94:95], v[246:247]
	v_pk_fma_f32 v[248:249], v[244:245], v[96:97], v[248:249]
	ds_read_b128 v[242:245], v57 offset:17312
	v_add_f32_e32 v250, v250, v202
	v_pk_fma_f32 v[246:247], v[190:191], v[98:99], v[246:247]
	v_pk_fma_f32 v[248:249], v[192:193], v[100:101], v[248:249]
	ds_read_b128 v[190:193], v57 offset:17328
	v_add_f32_e32 v250, v250, v111
	v_pk_fma_f32 v[246:247], v[194:195], v[102:103], v[246:247]
	v_pk_fma_f32 v[248:249], v[196:197], v[104:105], v[248:249]
	ds_read_b128 v[194:197], v57 offset:17344
	v_fma_f32 v111, v226, v227, -v250
	v_pk_fma_f32 v[246:247], v[198:199], v[106:107], v[246:247]
	v_pk_fma_f32 v[248:249], v[200:201], v[108:109], v[248:249]
	ds_read_b128 v[198:201], v57 offset:17360
	s_waitcnt lgkmcnt(5)
	v_pk_fma_f32 v[246:247], v[206:207], v[110:111], v[246:247]
	v_pk_fma_f32 v[248:249], v[208:209], v[112:113], v[248:249]
	ds_read_b128 v[206:209], v57 offset:17376
	v_mad_u32_u24 v61, v55, 63, v51
	ds_read_u16 v221, v61
	ds_read_b32 v220, v53 offset:252
	v_pk_fma_f32 v[250:251], v[210:211], v[34:35], 0 op_sel_hi:[1,1,0]
	v_pk_fma_f32 v[202:203], v[212:213], v[36:37], 0 op_sel_hi:[1,1,0]
	v_add_f32_e32 v246, v246, v247
	v_pk_fma_f32 v[250:251], v[214:215], v[86:87], v[250:251]
	v_pk_fma_f32 v[202:203], v[216:217], v[88:89], v[202:203]
	v_add_f32_e32 v248, v248, v249
	s_waitcnt lgkmcnt(5)
	v_pk_fma_f32 v[250:251], v[238:239], v[90:91], v[250:251]
	v_pk_fma_f32 v[202:203], v[240:241], v[92:93], v[202:203]
	v_lshlrev_b32_e32 v59, 16, v59
	v_pk_fma_f32 v[250:251], v[242:243], v[94:95], v[250:251]
	v_pk_fma_f32 v[202:203], v[244:245], v[96:97], v[202:203]
	v_add_f32_e32 v246, v246, v248
	v_pk_fma_f32 v[250:251], v[190:191], v[98:99], v[250:251]
	v_pk_fma_f32 v[202:203], v[192:193], v[100:101], v[202:203]
	v_add_f32_e32 v246, v246, v112
	s_waitcnt lgkmcnt(4)
	v_pk_fma_f32 v[250:251], v[194:195], v[102:103], v[250:251]
	v_pk_fma_f32 v[202:203], v[196:197], v[104:105], v[202:203]
	v_fma_f32 v112, v204, v59, -v246
	s_waitcnt lgkmcnt(3)
	v_pk_fma_f32 v[250:251], v[198:199], v[106:107], v[250:251]
	v_pk_fma_f32 v[202:203], v[200:201], v[108:109], v[202:203]
	s_waitcnt lgkmcnt(2)
	v_pk_fma_f32 v[250:251], v[206:207], v[110:111], v[250:251]
	v_pk_fma_f32 v[202:203], v[208:209], v[112:113], v[202:203]
	v_add_f32_e32 v250, v250, v251
	v_add_f32_e32 v202, v202, v203
	s_waitcnt lgkmcnt(0)
	v_lshlrev_b32_e32 v221, 16, v221
	v_add_f32_e32 v250, v250, v202
	v_add_f32_e32 v250, v250, v113
	v_fma_f32 v2, v220, v221, -v250
	s_and_saveexec_b64 s[0:1], vcc
	s_xor_b64 s[0:1], exec, s[0:1]
	s_cbranch_execz .LBB0_194
	v_lshl_add_u32 v47, v47, 1, 0
	v_bfe_u32 v49, v0, 16, 1
	v_add_u32_e32 v47, 0x1d900, v47
	v_add3_u32 v0, v0, v49, s33
	ds_write_b16_d16_hi v47, v0
	v_bfe_u32 v0, v3, 16, 1
	v_add3_u32 v0, v3, v0, s33
	ds_write_b16_d16_hi v47, v0 offset:256
	v_bfe_u32 v0, v4, 16, 1
	v_add3_u32 v0, v4, v0, s33
	ds_write_b16_d16_hi v47, v0 offset:512
	v_bfe_u32 v0, v5, 16, 1
	v_add3_u32 v0, v5, v0, s33
	ds_write_b16_d16_hi v47, v0 offset:768
	v_bfe_u32 v0, v6, 16, 1
	v_add3_u32 v0, v6, v0, s33
	ds_write_b16_d16_hi v47, v0 offset:1024
	v_bfe_u32 v0, v7, 16, 1
	v_add3_u32 v0, v7, v0, s33
	ds_write_b16_d16_hi v47, v0 offset:1280
	v_bfe_u32 v0, v8, 16, 1
	v_add3_u32 v0, v8, v0, s33
	ds_write_b16_d16_hi v47, v0 offset:1536
	v_bfe_u32 v0, v9, 16, 1
	v_add3_u32 v0, v9, v0, s33
	ds_write_b16_d16_hi v47, v0 offset:1792
	v_bfe_u32 v0, v10, 16, 1
	v_add3_u32 v0, v10, v0, s33
	ds_write_b16_d16_hi v47, v0 offset:2048
	v_bfe_u32 v0, v11, 16, 1
	v_add3_u32 v0, v11, v0, s33
	ds_write_b16_d16_hi v47, v0 offset:2304
	v_bfe_u32 v0, v12, 16, 1
	v_add3_u32 v0, v12, v0, s33
	ds_write_b16_d16_hi v47, v0 offset:2560
	v_bfe_u32 v0, v13, 16, 1
	v_add3_u32 v0, v13, v0, s33
	ds_write_b16_d16_hi v47, v0 offset:2816
	v_bfe_u32 v0, v14, 16, 1
	v_add3_u32 v0, v14, v0, s33
	ds_write_b16_d16_hi v47, v0 offset:3072
	v_bfe_u32 v0, v15, 16, 1
	v_add3_u32 v0, v15, v0, s33
	ds_write_b16_d16_hi v47, v0 offset:3328
	v_bfe_u32 v0, v16, 16, 1
	v_add3_u32 v0, v16, v0, s33
	ds_write_b16_d16_hi v47, v0 offset:3584
	v_bfe_u32 v0, v17, 16, 1
	v_add3_u32 v0, v17, v0, s33
	ds_write_b16_d16_hi v47, v0 offset:3840
	v_bfe_u32 v0, v18, 16, 1
	v_add3_u32 v0, v18, v0, s33
	ds_write_b16_d16_hi v47, v0 offset:4096
	v_bfe_u32 v0, v19, 16, 1
	v_add3_u32 v0, v19, v0, s33
	ds_write_b16_d16_hi v47, v0 offset:4352
	v_bfe_u32 v0, v20, 16, 1
	v_add3_u32 v0, v20, v0, s33
	ds_write_b16_d16_hi v47, v0 offset:4608
	v_bfe_u32 v0, v21, 16, 1
	v_add3_u32 v0, v21, v0, s33
	ds_write_b16_d16_hi v47, v0 offset:4864
	v_bfe_u32 v0, v22, 16, 1
	v_add3_u32 v0, v22, v0, s33
	ds_write_b16_d16_hi v47, v0 offset:5120
	v_bfe_u32 v0, v23, 16, 1
	v_add3_u32 v0, v23, v0, s33
	ds_write_b16_d16_hi v47, v0 offset:5376
	v_bfe_u32 v0, v24, 16, 1
	v_add3_u32 v0, v24, v0, s33
	ds_write_b16_d16_hi v47, v0 offset:5632
	v_bfe_u32 v0, v25, 16, 1
	v_add3_u32 v0, v25, v0, s33
	ds_write_b16_d16_hi v47, v0 offset:5888
	v_bfe_u32 v0, v26, 16, 1
	v_add3_u32 v0, v26, v0, s33
	ds_write_b16_d16_hi v47, v0 offset:6144
	v_bfe_u32 v0, v27, 16, 1
	v_add3_u32 v0, v27, v0, s33
	ds_write_b16_d16_hi v47, v0 offset:6400
	v_bfe_u32 v0, v28, 16, 1
	v_add3_u32 v0, v28, v0, s33
	ds_write_b16_d16_hi v47, v0 offset:6656
	v_bfe_u32 v0, v29, 16, 1
	v_add3_u32 v0, v29, v0, s33
	ds_write_b16_d16_hi v47, v0 offset:6912
	v_bfe_u32 v0, v30, 16, 1
	v_add3_u32 v0, v30, v0, s33
	ds_write_b16_d16_hi v47, v0 offset:7168
	v_bfe_u32 v0, v31, 16, 1
	v_add3_u32 v0, v31, v0, s33
	ds_write_b16_d16_hi v47, v0 offset:7424
	v_bfe_u32 v0, v32, 16, 1
	v_add3_u32 v0, v32, v0, s33
	ds_write_b16_d16_hi v47, v0 offset:7680
	v_bfe_u32 v0, v33, 16, 1
	v_add3_u32 v0, v33, v0, s33
	ds_write_b16_d16_hi v47, v0 offset:7936
	v_bfe_u32 v0, v34, 16, 1
	v_add3_u32 v0, v34, v0, s33
	ds_write_b16_d16_hi v47, v0 offset:8192
	v_bfe_u32 v0, v35, 16, 1
	v_add3_u32 v0, v35, v0, s33
	ds_write_b16_d16_hi v47, v0 offset:8448
	v_bfe_u32 v0, v36, 16, 1
	v_add3_u32 v0, v36, v0, s33
	ds_write_b16_d16_hi v47, v0 offset:8704
	v_bfe_u32 v0, v37, 16, 1
	v_add3_u32 v0, v37, v0, s33
	ds_write_b16_d16_hi v47, v0 offset:8960
	v_bfe_u32 v0, v86, 16, 1
	v_add3_u32 v0, v86, v0, s33
	ds_write_b16_d16_hi v47, v0 offset:9216
	v_bfe_u32 v0, v87, 16, 1
	v_add3_u32 v0, v87, v0, s33
	ds_write_b16_d16_hi v47, v0 offset:9472
	v_bfe_u32 v0, v88, 16, 1
	v_add3_u32 v0, v88, v0, s33
	ds_write_b16_d16_hi v47, v0 offset:9728
	v_bfe_u32 v0, v89, 16, 1
	v_add3_u32 v0, v89, v0, s33
	ds_write_b16_d16_hi v47, v0 offset:9984
	v_bfe_u32 v0, v90, 16, 1
	v_add3_u32 v0, v90, v0, s33
	ds_write_b16_d16_hi v47, v0 offset:10240
	v_bfe_u32 v0, v91, 16, 1
	v_add3_u32 v0, v91, v0, s33
	ds_write_b16_d16_hi v47, v0 offset:10496
	v_bfe_u32 v0, v92, 16, 1
	v_add3_u32 v0, v92, v0, s33
	ds_write_b16_d16_hi v47, v0 offset:10752
	v_bfe_u32 v0, v93, 16, 1
	v_add3_u32 v0, v93, v0, s33
	ds_write_b16_d16_hi v47, v0 offset:11008
	v_bfe_u32 v0, v94, 16, 1
	v_add3_u32 v0, v94, v0, s33
	ds_write_b16_d16_hi v47, v0 offset:11264
	v_bfe_u32 v0, v95, 16, 1
	v_add3_u32 v0, v95, v0, s33
	ds_write_b16_d16_hi v47, v0 offset:11520
	v_bfe_u32 v0, v96, 16, 1
	v_add3_u32 v0, v96, v0, s33
	ds_write_b16_d16_hi v47, v0 offset:11776
	v_bfe_u32 v0, v97, 16, 1
	v_add3_u32 v0, v97, v0, s33
	ds_write_b16_d16_hi v47, v0 offset:12032
	v_bfe_u32 v0, v98, 16, 1
	v_add3_u32 v0, v98, v0, s33
	ds_write_b16_d16_hi v47, v0 offset:12288
	v_bfe_u32 v0, v99, 16, 1
	v_add3_u32 v0, v99, v0, s33
	ds_write_b16_d16_hi v47, v0 offset:12544
	v_bfe_u32 v0, v100, 16, 1
	v_add3_u32 v0, v100, v0, s33
	ds_write_b16_d16_hi v47, v0 offset:12800
	v_bfe_u32 v0, v101, 16, 1
	v_add3_u32 v0, v101, v0, s33
	ds_write_b16_d16_hi v47, v0 offset:13056
	v_bfe_u32 v0, v102, 16, 1
	v_add3_u32 v0, v102, v0, s33
	ds_write_b16_d16_hi v47, v0 offset:13312
	v_bfe_u32 v0, v103, 16, 1
	v_add3_u32 v0, v103, v0, s33
	ds_write_b16_d16_hi v47, v0 offset:13568
	v_bfe_u32 v0, v104, 16, 1
	v_add3_u32 v0, v104, v0, s33
	ds_write_b16_d16_hi v47, v0 offset:13824
	v_bfe_u32 v0, v105, 16, 1
	v_add3_u32 v0, v105, v0, s33
	ds_write_b16_d16_hi v47, v0 offset:14080
	v_bfe_u32 v0, v106, 16, 1
	v_add3_u32 v0, v106, v0, s33
	ds_write_b16_d16_hi v47, v0 offset:14336
	v_bfe_u32 v0, v107, 16, 1
	v_add3_u32 v0, v107, v0, s33
	ds_write_b16_d16_hi v47, v0 offset:14592
	v_bfe_u32 v0, v108, 16, 1
	v_add3_u32 v0, v108, v0, s33
	ds_write_b16_d16_hi v47, v0 offset:14848
	v_bfe_u32 v0, v109, 16, 1
	v_add3_u32 v0, v109, v0, s33
	ds_write_b16_d16_hi v47, v0 offset:15104
	v_bfe_u32 v0, v110, 16, 1
	v_add3_u32 v0, v110, v0, s33
	ds_write_b16_d16_hi v47, v0 offset:15360
	v_bfe_u32 v0, v111, 16, 1
	v_add3_u32 v0, v111, v0, s33
	ds_write_b16_d16_hi v47, v0 offset:15616
	v_bfe_u32 v0, v112, 16, 1
	v_add3_u32 v0, v112, v0, s33
	ds_write_b16_d16_hi v47, v0 offset:15872
	v_bfe_u32 v0, v2, 16, 1
	v_add3_u32 v0, v2, v0, s33
	ds_write_b16_d16_hi v47, v0 offset:16128
